# LRU conv segment: interior tiles branch around the out-of-range row zeroing (on top of priority scheme + carry trims)
# speedup vs baseline: 1.0103x; 1.0103x over previous
; #define LAS __attribute__((address_space(3)))
; __device__ __forceinline__ unsigned cvt_pk_bf16(float lo, float hi) { unsigned r; asm volatile("v_cvt_pk_bf16_f32 %0, %1, %2" : "=v"(r) : "v"(lo), "v"(hi)); return r; }
; __device__ __forceinline__ float bf_lo(unsigned u) { return __uint_as_float(u << 16); }
; __device__ __forceinline__ float bf_hi(unsigned u) { return __uint_as_float(u & 0xffff0000u); }
; template <int dir>
; __device__ __forceinline__ void lru_pass(LAS unsigned char* lds, const Params& P, int b, int h, int q, bool dry) {
;     ...
;         for (int sc = 0; sc < 9; ++sc) {
;             const bool isctx = (sc == 0);
;             const int t0 = cur.t0;
; #pragma unroll
;             for (int j = 0; j < 11; ++j) { if (j != 0 && j < 9) continue;
;                 const int t = t0 + tr * 8 - 1 + j; if (t < 0 || t >= cur.L) rows[j] = (u32x4){0u, 0u, 0u, 0u}; }
;             f32x2 cw2[4][4], cb2[4];
; #pragma unroll
;             for (int k = 0; k < 5; ++k) { const f32x4 a = *(const LAS f32x4*)(CWL + k * 128 + cgp * 8), c2 = *(const LAS f32x4*)(CWL + k * 128 + cgp * 8 + 4);
;                 if (k < 4) { cw2[k][0] = (f32x2){a[0], a[1]}; cw2[k][1] = (f32x2){a[2], a[3]}; cw2[k][2] = (f32x2){c2[0], c2[1]}; cw2[k][3] = (f32x2){c2[2], c2[3]}; }
;                 else { cb2[0] = (f32x2){a[0], a[1]}; cb2[1] = (f32x2){a[2], a[3]}; cb2[2] = (f32x2){c2[0], c2[1]}; cb2[3] = (f32x2){c2[2], c2[3]}; } }
; #pragma unroll
;             for (int j = 0; j < 8; ++j) {
;                 f32x2 o0 = cb2[0], o1 = cb2[1], o2 = cb2[2], o3 = cb2[3];
; #pragma unroll
;                 for (int k = 0; k < 4; ++k) { const u32x4 rr = rows[j + k];
;                     o0 = cw2[k][0] * (f32x2){bf_lo(rr.x), bf_hi(rr.x)} + o0; o1 = cw2[k][1] * (f32x2){bf_lo(rr.y), bf_hi(rr.y)} + o1;
;                     o2 = cw2[k][2] * (f32x2){bf_lo(rr.z), bf_hi(rr.z)} + o2; o3 = cw2[k][3] * (f32x2){bf_lo(rr.w), bf_hi(rr.w)} + o3; }
;                 u32x4 w; w.x = cvt_pk_bf16(o0[0], o0[1]); w.y = cvt_pk_bf16(o1[0], o1[1]); w.z = cvt_pk_bf16(o2[0], o2[1]); w.w = cvt_pk_bf16(o3[0], o3[1]);
;                 *(LAS u32x4*)(XC + (tr * 8 + j) * XC_PITCH + cgp * 16) = w;
;             }
.Lpp_f_nox:
.LBB0_292:
	s_cmp_lg_u32 s97, 0
	s_cselect_b32 s42, 1, 0
	s_add_i32 s18, s97, 0x102
	s_cmp_le_i32 s18, s92
	s_cselect_b32 s18, 1, 0
	s_and_b32 s42, s42, s18
	s_cmp_lg_u32 s42, 0
	s_cbranch_scc1 .Lmsk_f_in
	v_add_u32_e32 v32, s97, v139
	v_cmp_lt_i32_e64 s[18:19], -1, v32
	v_cmp_gt_i32_e64 s[20:21], s92, v32
	s_and_b64 s[18:19], s[18:19], s[20:21]
	v_add_u32_e32 v33, 9, v32
	s_waitcnt vmcnt(10)
	v_cndmask_b32_e64 v71, 0, v71, s[18:19]
	v_cndmask_b32_e64 v70, 0, v70, s[18:19]
	v_cndmask_b32_e64 v69, 0, v69, s[18:19]
	v_cndmask_b32_e64 v68, 0, v68, s[18:19]
	v_cmp_lt_i32_e64 s[18:19], -10, v32
	v_cmp_gt_i32_e64 s[20:21], s92, v33
	s_and_b64 s[18:19], s[18:19], s[20:21]
	v_add_u32_e32 v33, 10, v32
	s_waitcnt vmcnt(1)
	v_cndmask_b32_e64 v107, 0, v107, s[18:19]
	v_cndmask_b32_e64 v106, 0, v106, s[18:19]
	v_cndmask_b32_e64 v105, 0, v105, s[18:19]
	v_cndmask_b32_e64 v104, 0, v104, s[18:19]
	v_cmp_lt_i32_e64 s[18:19], -11, v32
	v_cmp_gt_i32_e64 s[20:21], s92, v33
	s_branch .Lmsk_f_j
.Lmsk_f_in:
	s_mov_b64 s[18:19], -1
	s_mov_b64 s[20:21], -1
	s_waitcnt vmcnt(1)
.Lmsk_f_j:
	ds_read_b128 v[60:63], v150
	ds_read_b128 v[52:55], v150 offset:16
	ds_read_b128 v[44:47], v150 offset:528
	ds_read_b128 v[56:59], v150 offset:512
	ds_read_b128 v[40:43], v150 offset:1040
	ds_read_b128 v[48:51], v150 offset:1024
	ds_read_b128 v[120:123], v150 offset:2064
	ds_read_b128 v[124:127], v150 offset:2048
	ds_read_b128 v[32:35], v150 offset:1552
	ds_read_b128 v[36:39], v150 offset:1536
	v_lshlrev_b32_e32 v66, 16, v68
	v_and_b32_e32 v67, 0xffff0000, v68
	v_lshlrev_b32_e32 v154, 16, v69
	v_and_b32_e32 v155, 0xffff0000, v69
	v_lshlrev_b32_e32 v168, 16, v70
	v_and_b32_e32 v169, 0xffff0000, v70
	s_waitcnt lgkmcnt(2)
	v_pk_fma_f32 v[66:67], v[60:61], v[66:67], v[124:125]
	v_pk_fma_f32 v[154:155], v[62:63], v[154:155], v[126:127]
	v_pk_fma_f32 v[168:169], v[52:53], v[168:169], v[120:121]
	v_lshlrev_b32_e32 v170, 16, v71
	v_and_b32_e32 v171, 0xffff0000, v71
	v_lshlrev_b32_e32 v172, 16, v72
	v_and_b32_e32 v173, 0xffff0000, v72
	v_lshlrev_b32_e32 v174, 16, v73
	v_and_b32_e32 v175, 0xffff0000, v73
	v_lshlrev_b32_e32 v176, 16, v74
	v_and_b32_e32 v177, 0xffff0000, v74
	v_pk_fma_f32 v[170:171], v[54:55], v[170:171], v[122:123]
	v_pk_fma_f32 v[66:67], v[56:57], v[172:173], v[66:67]
	v_pk_fma_f32 v[154:155], v[58:59], v[174:175], v[154:155]
	v_pk_fma_f32 v[168:169], v[44:45], v[176:177], v[168:169]
	v_lshlrev_b32_e32 v178, 16, v75
	v_and_b32_e32 v179, 0xffff0000, v75
	v_lshlrev_b32_e32 v180, 16, v76
	v_and_b32_e32 v181, 0xffff0000, v76
	v_lshlrev_b32_e32 v182, 16, v77
	v_and_b32_e32 v183, 0xffff0000, v77
	v_lshlrev_b32_e32 v184, 16, v78
	v_and_b32_e32 v185, 0xffff0000, v78
	v_pk_fma_f32 v[170:171], v[46:47], v[178:179], v[170:171]
	v_pk_fma_f32 v[66:67], v[48:49], v[180:181], v[66:67]
	v_pk_fma_f32 v[154:155], v[50:51], v[182:183], v[154:155]
	v_pk_fma_f32 v[168:169], v[40:41], v[184:185], v[168:169]
	v_lshlrev_b32_e32 v186, 16, v79
	v_and_b32_e32 v187, 0xffff0000, v79
	v_lshlrev_b32_e32 v188, 16, v80
	v_and_b32_e32 v189, 0xffff0000, v80
	v_lshlrev_b32_e32 v190, 16, v81
	v_and_b32_e32 v191, 0xffff0000, v81
	v_lshlrev_b32_e32 v192, 16, v82
	v_and_b32_e32 v193, 0xffff0000, v82
	v_pk_fma_f32 v[170:171], v[42:43], v[186:187], v[170:171]
	s_waitcnt lgkmcnt(0)
	v_pk_fma_f32 v[66:67], v[36:37], v[188:189], v[66:67]
	v_pk_fma_f32 v[154:155], v[38:39], v[190:191], v[154:155]
	v_pk_fma_f32 v[194:195], v[32:33], v[192:193], v[168:169]
	v_lshlrev_b32_e32 v196, 16, v83
	v_and_b32_e32 v197, 0xffff0000, v83
	v_cvt_pk_bf16_f32 v168, v66, v67
	v_cvt_pk_bf16_f32 v169, v154, v155
	v_pk_fma_f32 v[198:199], v[34:35], v[196:197], v[170:171]
	v_cvt_pk_bf16_f32 v170, v194, v195
	v_pk_fma_f32 v[66:67], v[60:61], v[172:173], v[124:125]
	v_cvt_pk_bf16_f32 v171, v198, v199
	ds_write_b128 v151, v[168:171]
	v_pk_fma_f32 v[154:155], v[62:63], v[174:175], v[126:127]
	v_pk_fma_f32 v[168:169], v[52:53], v[176:177], v[120:121]
	v_pk_fma_f32 v[170:171], v[54:55], v[178:179], v[122:123]
	v_pk_fma_f32 v[66:67], v[56:57], v[180:181], v[66:67]
	v_pk_fma_f32 v[154:155], v[58:59], v[182:183], v[154:155]
	v_pk_fma_f32 v[168:169], v[44:45], v[184:185], v[168:169]
	v_pk_fma_f32 v[170:171], v[46:47], v[186:187], v[170:171]
	v_pk_fma_f32 v[66:67], v[48:49], v[188:189], v[66:67]
	v_pk_fma_f32 v[154:155], v[50:51], v[190:191], v[154:155]
	v_pk_fma_f32 v[168:169], v[40:41], v[192:193], v[168:169]
	v_lshlrev_b32_e32 v172, 16, v84
	v_and_b32_e32 v173, 0xffff0000, v84
	v_lshlrev_b32_e32 v174, 16, v85
	v_and_b32_e32 v175, 0xffff0000, v85
	v_lshlrev_b32_e32 v176, 16, v86
	v_and_b32_e32 v177, 0xffff0000, v86
	v_pk_fma_f32 v[170:171], v[42:43], v[196:197], v[170:171]
	v_pk_fma_f32 v[66:67], v[36:37], v[172:173], v[66:67]
	v_pk_fma_f32 v[154:155], v[38:39], v[174:175], v[154:155]
	v_pk_fma_f32 v[178:179], v[32:33], v[176:177], v[168:169]
	v_lshlrev_b32_e32 v194, 16, v87
	v_and_b32_e32 v195, 0xffff0000, v87
	v_cvt_pk_bf16_f32 v168, v66, v67
	v_cvt_pk_bf16_f32 v169, v154, v155
	v_pk_fma_f32 v[198:199], v[34:35], v[194:195], v[170:171]
	v_cvt_pk_bf16_f32 v170, v178, v179
	v_pk_fma_f32 v[66:67], v[60:61], v[180:181], v[124:125]
	v_cvt_pk_bf16_f32 v171, v198, v199
	ds_write_b128 v151, v[168:171] offset:272
	v_pk_fma_f32 v[154:155], v[62:63], v[182:183], v[126:127]
	v_pk_fma_f32 v[168:169], v[52:53], v[184:185], v[120:121]
	v_pk_fma_f32 v[170:171], v[54:55], v[186:187], v[122:123]
	v_pk_fma_f32 v[66:67], v[56:57], v[188:189], v[66:67]
	v_pk_fma_f32 v[154:155], v[58:59], v[190:191], v[154:155]
	v_pk_fma_f32 v[168:169], v[44:45], v[192:193], v[168:169]
	v_pk_fma_f32 v[170:171], v[46:47], v[196:197], v[170:171]
; #define LAS __attribute__((address_space(3)))
; __device__ __forceinline__ unsigned cvt_pk_bf16(float lo, float hi) { unsigned r; asm volatile("v_cvt_pk_bf16_f32 %0, %1, %2" : "=v"(r) : "v"(lo), "v"(hi)); return r; }
; __device__ __forceinline__ float bf_lo(unsigned u) { return __uint_as_float(u << 16); }
; __device__ __forceinline__ float bf_hi(unsigned u) { return __uint_as_float(u & 0xffff0000u); }
; template <int dir>
; __device__ __forceinline__ void lru_pass(LAS unsigned char* lds, const Params& P, int b, int h, int q, bool dry) {
;     ...
;             for (int j = 0; j < 8; ++j) {
;                 f32x2 o0 = cb2[0], o1 = cb2[1], o2 = cb2[2], o3 = cb2[3];
; #pragma unroll
;                 for (int k = 0; k < 4; ++k) { const u32x4 rr = rows[j + k];
;                     o0 = cw2[k][0] * (f32x2){bf_lo(rr.x), bf_hi(rr.x)} + o0; o1 = cw2[k][1] * (f32x2){bf_lo(rr.y), bf_hi(rr.y)} + o1;
;                     o2 = cw2[k][2] * (f32x2){bf_lo(rr.z), bf_hi(rr.z)} + o2; o3 = cw2[k][3] * (f32x2){bf_lo(rr.w), bf_hi(rr.w)} + o3; }
;                 u32x4 w; w.x = cvt_pk_bf16(o0[0], o0[1]); w.y = cvt_pk_bf16(o1[0], o1[1]); w.z = cvt_pk_bf16(o2[0], o2[1]); w.w = cvt_pk_bf16(o3[0], o3[1]);
;                 *(LAS u32x4*)(XC + (tr * 8 + j) * XC_PITCH + cgp * 16) = w;
;             }
	v_pk_fma_f32 v[66:67], v[48:49], v[172:173], v[66:67]
	v_pk_fma_f32 v[154:155], v[50:51], v[174:175], v[154:155]
	v_pk_fma_f32 v[168:169], v[40:41], v[176:177], v[168:169]
	v_lshlrev_b32_e32 v178, 16, v88
	v_and_b32_e32 v179, 0xffff0000, v88
	v_lshlrev_b32_e32 v180, 16, v89
	v_and_b32_e32 v181, 0xffff0000, v89
	v_lshlrev_b32_e32 v182, 16, v90
	v_and_b32_e32 v183, 0xffff0000, v90
	v_pk_fma_f32 v[170:171], v[42:43], v[194:195], v[170:171]
	v_pk_fma_f32 v[66:67], v[36:37], v[178:179], v[66:67]
	v_pk_fma_f32 v[154:155], v[38:39], v[180:181], v[154:155]
	v_pk_fma_f32 v[184:185], v[32:33], v[182:183], v[168:169]
	v_lshlrev_b32_e32 v186, 16, v91
	v_and_b32_e32 v187, 0xffff0000, v91
	v_cvt_pk_bf16_f32 v168, v66, v67
	v_cvt_pk_bf16_f32 v169, v154, v155
	v_pk_fma_f32 v[198:199], v[34:35], v[186:187], v[170:171]
	v_cvt_pk_bf16_f32 v170, v184, v185
	v_pk_fma_f32 v[66:67], v[60:61], v[188:189], v[124:125]
	v_cvt_pk_bf16_f32 v171, v198, v199
	ds_write_b128 v151, v[168:171] offset:544
	v_pk_fma_f32 v[154:155], v[62:63], v[190:191], v[126:127]
	v_pk_fma_f32 v[168:169], v[52:53], v[192:193], v[120:121]
	v_pk_fma_f32 v[170:171], v[54:55], v[196:197], v[122:123]
	v_pk_fma_f32 v[66:67], v[56:57], v[172:173], v[66:67]
	v_pk_fma_f32 v[154:155], v[58:59], v[174:175], v[154:155]
	v_pk_fma_f32 v[168:169], v[44:45], v[176:177], v[168:169]
	v_pk_fma_f32 v[170:171], v[46:47], v[194:195], v[170:171]
	v_pk_fma_f32 v[66:67], v[48:49], v[178:179], v[66:67]
	v_pk_fma_f32 v[154:155], v[50:51], v[180:181], v[154:155]
	v_pk_fma_f32 v[168:169], v[40:41], v[182:183], v[168:169]
	v_lshlrev_b32_e32 v184, 16, v92
	v_and_b32_e32 v185, 0xffff0000, v92
	v_lshlrev_b32_e32 v188, 16, v93
	v_and_b32_e32 v189, 0xffff0000, v93
	v_lshlrev_b32_e32 v190, 16, v94
	v_and_b32_e32 v191, 0xffff0000, v94
	v_pk_fma_f32 v[170:171], v[42:43], v[186:187], v[170:171]
	v_pk_fma_f32 v[66:67], v[36:37], v[184:185], v[66:67]
	v_pk_fma_f32 v[154:155], v[38:39], v[188:189], v[154:155]
	v_pk_fma_f32 v[192:193], v[32:33], v[190:191], v[168:169]
	v_lshlrev_b32_e32 v196, 16, v95
	v_and_b32_e32 v197, 0xffff0000, v95
	v_cvt_pk_bf16_f32 v168, v66, v67
	v_cvt_pk_bf16_f32 v169, v154, v155
	v_pk_fma_f32 v[198:199], v[34:35], v[196:197], v[170:171]
	v_cvt_pk_bf16_f32 v170, v192, v193
	v_pk_fma_f32 v[66:67], v[60:61], v[172:173], v[124:125]
	v_cvt_pk_bf16_f32 v171, v198, v199
	ds_write_b128 v151, v[168:171] offset:816
	v_pk_fma_f32 v[154:155], v[62:63], v[174:175], v[126:127]
	v_pk_fma_f32 v[168:169], v[52:53], v[176:177], v[120:121]
	v_pk_fma_f32 v[170:171], v[54:55], v[194:195], v[122:123]
	v_pk_fma_f32 v[66:67], v[56:57], v[178:179], v[66:67]
	v_pk_fma_f32 v[154:155], v[58:59], v[180:181], v[154:155]
	v_pk_fma_f32 v[168:169], v[44:45], v[182:183], v[168:169]
	v_pk_fma_f32 v[170:171], v[46:47], v[186:187], v[170:171]
	v_pk_fma_f32 v[66:67], v[48:49], v[184:185], v[66:67]
	v_pk_fma_f32 v[154:155], v[50:51], v[188:189], v[154:155]
	v_pk_fma_f32 v[168:169], v[40:41], v[190:191], v[168:169]
	v_lshlrev_b32_e32 v172, 16, v96
	v_and_b32_e32 v173, 0xffff0000, v96
	v_lshlrev_b32_e32 v174, 16, v97
	v_and_b32_e32 v175, 0xffff0000, v97
	v_lshlrev_b32_e32 v176, 16, v98
	v_and_b32_e32 v177, 0xffff0000, v98
	v_pk_fma_f32 v[170:171], v[42:43], v[196:197], v[170:171]
	v_pk_fma_f32 v[66:67], v[36:37], v[172:173], v[66:67]
	v_pk_fma_f32 v[154:155], v[38:39], v[174:175], v[154:155]
	v_pk_fma_f32 v[192:193], v[32:33], v[176:177], v[168:169]
	v_lshlrev_b32_e32 v194, 16, v99
	v_and_b32_e32 v195, 0xffff0000, v99
	v_cvt_pk_bf16_f32 v168, v66, v67
	v_cvt_pk_bf16_f32 v169, v154, v155
	v_pk_fma_f32 v[198:199], v[34:35], v[194:195], v[170:171]
	v_cvt_pk_bf16_f32 v170, v192, v193
	v_pk_fma_f32 v[66:67], v[60:61], v[178:179], v[124:125]
	v_cvt_pk_bf16_f32 v171, v198, v199
	ds_write_b128 v151, v[168:171] offset:1088
	v_pk_fma_f32 v[154:155], v[62:63], v[180:181], v[126:127]
	v_pk_fma_f32 v[168:169], v[52:53], v[182:183], v[120:121]
	v_pk_fma_f32 v[170:171], v[54:55], v[186:187], v[122:123]
	v_pk_fma_f32 v[66:67], v[56:57], v[184:185], v[66:67]
	v_pk_fma_f32 v[154:155], v[58:59], v[188:189], v[154:155]
	v_pk_fma_f32 v[168:169], v[44:45], v[190:191], v[168:169]
	v_pk_fma_f32 v[170:171], v[46:47], v[196:197], v[170:171]
	v_pk_fma_f32 v[66:67], v[48:49], v[172:173], v[66:67]
	v_pk_fma_f32 v[154:155], v[50:51], v[174:175], v[154:155]
	v_pk_fma_f32 v[168:169], v[40:41], v[176:177], v[168:169]
	v_lshlrev_b32_e32 v178, 16, v100
	v_and_b32_e32 v179, 0xffff0000, v100
	v_lshlrev_b32_e32 v180, 16, v101
	v_and_b32_e32 v181, 0xffff0000, v101
	v_lshlrev_b32_e32 v182, 16, v102
	v_and_b32_e32 v183, 0xffff0000, v102
	v_pk_fma_f32 v[170:171], v[42:43], v[194:195], v[170:171]
	v_pk_fma_f32 v[66:67], v[36:37], v[178:179], v[66:67]
	v_pk_fma_f32 v[154:155], v[38:39], v[180:181], v[154:155]
	v_pk_fma_f32 v[186:187], v[32:33], v[182:183], v[168:169]
	v_lshlrev_b32_e32 v192, 16, v103
	v_and_b32_e32 v193, 0xffff0000, v103
	v_cvt_pk_bf16_f32 v168, v66, v67
	v_cvt_pk_bf16_f32 v169, v154, v155
	s_and_b64 s[18:19], s[18:19], s[20:21]
	v_pk_fma_f32 v[198:199], v[34:35], v[192:193], v[170:171]
	v_cvt_pk_bf16_f32 v170, v186, v187
	v_pk_fma_f32 v[66:67], v[60:61], v[184:185], v[124:125]
	v_cvt_pk_bf16_f32 v171, v198, v199
	ds_write_b128 v151, v[168:171] offset:1360
	v_pk_fma_f32 v[168:169], v[52:53], v[190:191], v[120:121]
	v_pk_fma_f32 v[60:61], v[60:61], v[172:173], v[124:125]
	v_pk_fma_f32 v[52:53], v[52:53], v[176:177], v[120:121]
	s_waitcnt vmcnt(0)
; #define LAS __attribute__((address_space(3)))
; __device__ __forceinline__ unsigned cvt_pk_bf16(float lo, float hi) { unsigned r; asm volatile("v_cvt_pk_bf16_f32 %0, %1, %2" : "=v"(r) : "v"(lo), "v"(hi)); return r; }
; __device__ __forceinline__ float bf_lo(unsigned u) { return __uint_as_float(u << 16); }
; __device__ __forceinline__ float bf_hi(unsigned u) { return __uint_as_float(u & 0xffff0000u); }
; template <int dir>
; __device__ __forceinline__ void lru_pass(LAS unsigned char* lds, const Params& P, int b, int h, int q, bool dry) {
;     ...
;             for (int j = 0; j < 8; ++j) {
;                 f32x2 o0 = cb2[0], o1 = cb2[1], o2 = cb2[2], o3 = cb2[3];
; #pragma unroll
;                 for (int k = 0; k < 4; ++k) { const u32x4 rr = rows[j + k];
;                     o0 = cw2[k][0] * (f32x2){bf_lo(rr.x), bf_hi(rr.x)} + o0; o1 = cw2[k][1] * (f32x2){bf_lo(rr.y), bf_hi(rr.y)} + o1;
;                     o2 = cw2[k][2] * (f32x2){bf_lo(rr.z), bf_hi(rr.z)} + o2; o3 = cw2[k][3] * (f32x2){bf_lo(rr.w), bf_hi(rr.w)} + o3; }
;                 u32x4 w; w.x = cvt_pk_bf16(o0[0], o0[1]); w.y = cvt_pk_bf16(o1[0], o1[1]); w.z = cvt_pk_bf16(o2[0], o2[1]); w.w = cvt_pk_bf16(o3[0], o3[1]);
;                 *(LAS u32x4*)(XC + (tr * 8 + j) * XC_PITCH + cgp * 16) = w;
;             }
;     ...
;             LruTile nxt = cur;
;             if (sc < 8) { nxt = lru_tile(Z, ZC, b, h, dir, sc + 1); lru_load_rows(rows, nxt, tr, cgp);
; #pragma unroll
;                 for (int i = 0; i < NIN; ++i) { const int id = tid + i * NTHREADS;
;                     if (dir == 0) inr[i] = *(const u32x4*)(Zg + (size_t)(nxt.t0 + (id >> 2)) * 128 + (id & 3) * 8);
;                     else inr[i] = *(const u32x4*)(Hg + (size_t)(nxt.t0 + (id >> 3)) * DM + (id & 7) * 4); } }
	v_cndmask_b32_e64 v108, 0, v108, s[18:19]
	v_pk_fma_f32 v[154:155], v[62:63], v[188:189], v[126:127]
	v_pk_fma_f32 v[66:67], v[56:57], v[172:173], v[66:67]
	v_pk_fma_f32 v[168:169], v[44:45], v[176:177], v[168:169]
	v_lshlrev_b32_e32 v184, 16, v104
	v_and_b32_e32 v185, 0xffff0000, v104
	v_lshlrev_b32_e32 v188, 16, v106
	v_and_b32_e32 v189, 0xffff0000, v106
	v_pk_fma_f32 v[62:63], v[62:63], v[174:175], v[126:127]
	v_pk_fma_f32 v[56:57], v[56:57], v[178:179], v[60:61]
	v_pk_fma_f32 v[44:45], v[44:45], v[182:183], v[52:53]
	v_cndmask_b32_e64 v109, 0, v109, s[18:19]
	v_pk_fma_f32 v[154:155], v[58:59], v[174:175], v[154:155]
	v_pk_fma_f32 v[66:67], v[48:49], v[178:179], v[66:67]
	v_pk_fma_f32 v[168:169], v[40:41], v[182:183], v[168:169]
	v_lshlrev_b32_e32 v186, 16, v105
	v_and_b32_e32 v187, 0xffff0000, v105
	v_pk_fma_f32 v[58:59], v[58:59], v[180:181], v[62:63]
	v_pk_fma_f32 v[48:49], v[48:49], v[184:185], v[56:57]
	v_pk_fma_f32 v[40:41], v[40:41], v[188:189], v[44:45]
	v_lshlrev_b32_e32 v44, 16, v108
	v_and_b32_e32 v45, 0xffff0000, v108
	v_cndmask_b32_e64 v110, 0, v110, s[18:19]
	v_pk_fma_f32 v[170:171], v[54:55], v[196:197], v[122:123]
	v_pk_fma_f32 v[154:155], v[50:51], v[180:181], v[154:155]
	v_pk_fma_f32 v[66:67], v[36:37], v[184:185], v[66:67]
	v_pk_fma_f32 v[54:55], v[54:55], v[194:195], v[122:123]
	v_pk_fma_f32 v[50:51], v[50:51], v[186:187], v[58:59]
	v_pk_fma_f32 v[36:37], v[36:37], v[44:45], v[48:49]
	v_lshlrev_b32_e32 v44, 16, v109
	v_and_b32_e32 v45, 0xffff0000, v109
	v_cndmask_b32_e64 v111, 0, v111, s[18:19]
	v_pk_fma_f32 v[170:171], v[46:47], v[194:195], v[170:171]
	v_pk_fma_f32 v[154:155], v[38:39], v[186:187], v[154:155]
	v_lshlrev_b32_e32 v196, 16, v107
	v_and_b32_e32 v197, 0xffff0000, v107
	v_pk_fma_f32 v[46:47], v[46:47], v[192:193], v[54:55]
	v_pk_fma_f32 v[38:39], v[38:39], v[44:45], v[50:51]
	v_lshlrev_b32_e32 v44, 16, v110
	v_and_b32_e32 v45, 0xffff0000, v110
	v_pk_fma_f32 v[170:171], v[42:43], v[192:193], v[170:171]
	v_pk_fma_f32 v[190:191], v[32:33], v[188:189], v[168:169]
	v_pk_fma_f32 v[42:43], v[42:43], v[196:197], v[46:47]
	v_pk_fma_f32 v[40:41], v[32:33], v[44:45], v[40:41]
	v_lshlrev_b32_e32 v32, 16, v111
	v_and_b32_e32 v33, 0xffff0000, v111
	v_pk_fma_f32 v[198:199], v[34:35], v[196:197], v[170:171]
	v_cvt_pk_bf16_f32 v168, v66, v67
	v_cvt_pk_bf16_f32 v169, v154, v155
	v_cvt_pk_bf16_f32 v170, v190, v191
	v_pk_fma_f32 v[42:43], v[34:35], v[32:33], v[42:43]
	v_cvt_pk_bf16_f32 v171, v198, v199
	ds_write_b128 v151, v[168:171] offset:1632
	v_cvt_pk_bf16_f32 v32, v36, v37
	v_cvt_pk_bf16_f32 v33, v38, v39
	v_cvt_pk_bf16_f32 v34, v40, v41
	v_cvt_pk_bf16_f32 v35, v42, v43
	s_cmp_eq_u32 s80, 0x80000
	ds_write_b128 v151, v[32:35] offset:1904
	ds_write_b128 v158, v[112:115]
	ds_write_b128 v159, v[116:119]
	s_cbranch_scc1 .LBB0_294
	v_lshl_add_u64 v[32:33], v[136:137], 0, s[80:81]
	global_load_dwordx4 v[68:71], v[32:33], off offset:-1280
	global_load_dwordx4 v[72:75], v[32:33], off offset:-1024
	global_load_dwordx4 v[76:79], v[32:33], off offset:-768
	global_load_dwordx4 v[80:83], v[32:33], off offset:-512
	global_load_dwordx4 v[84:87], v[32:33], off offset:-256
	global_load_dwordx4 v[88:91], v[32:33], off
	global_load_dwordx4 v[92:95], v[32:33], off offset:256
	global_load_dwordx4 v[96:99], v[32:33], off offset:512
	global_load_dwordx4 v[100:103], v[32:33], off offset:768
	global_load_dwordx4 v[104:107], v[32:33], off offset:1024
	v_lshl_add_u64 v[34:35], v[134:135], 0, s[80:81]
	global_load_dwordx4 v[108:111], v[32:33], off offset:1280
	global_load_dwordx4 v[112:115], v[34:35], off
	v_lshl_add_u64 v[32:33], v[132:133], 0, s[80:81]
	global_load_dwordx4 v[116:119], v[32:33], off
	s_movk_i32 s92, 0x800
	s_mov_b32 s20, s90
	s_branch .LBB0_295

; #define LAS __attribute__((address_space(3)))
; __device__ __forceinline__ int opaque_tid() { int t = threadIdx.x; asm volatile("" : "+v"(t)); return t; }
; template <int dir>
; __device__ __forceinline__ void lru_pass(LAS unsigned char* lds, const Params& P, int b, int h, int q, bool dry) {
;     const int tid = opaque_tid(), lane = tid & 63, wid = __builtin_amdgcn_readfirstlane(tid >> 6), g = lane >> 5, nl = lane & 31;
;     const int chl = q * 32 + nl, ch = h * 128 + chl;
;     LAS unsigned char* XC = lds;
;     LAS float* AGG = (LAS float*)(lds + 256 * XC_PITCH);
;     LAS unsigned char* WB = lds + 256 * XC_PITCH + 2048;
;     LAS float* CWL = (LAS float*)(lds + 256 * XC_PITCH + 2048 + 64 * XC_PITCH);
;     LAS unsigned char* TIN = lds + LRU_IO_OFF;
;     LAS unsigned char* TOUT = lds + LRU_IO_OFF + 256 * (dir == 0 ? IO_NP : IO_WP);
;     bf16_t* Z = (bf16_t*)(P.ws + WS_Z); const bf16_t* ZC = (const bf16_t*)(P.ws + WS_ZC); unsigned* HFW = (unsigned*)(P.ws + WS_HF);
;     const bf16_t* LruW = (const bf16_t*)(P.ws + WS_LRUW);
;     const int cgp = tid & 15, tr = tid >> 4;
;     const int s_i = 16 * ((nl >> 2) & 1) + ((nl >> 3) << 2) + (nl & 3);
;     const bf16_t* Zg = Z + ZSLAB(8 + h, (size_t)b * SEQ) + q * 32;
;     unsigned* Hg = HFW + (size_t)b * SEQ * DM + h * 128 + q * 32;
;     {
; #pragma unroll
;         for (int i = 0; i < 2; ++i) { const int idx = tid + i * NTHREADS, gate = idx >> 9, n = (idx >> 4) & 31, kc = idx & 15;
;             *(LAS u32x4*)(WB + (gate * 32 + n) * XC_PITCH + kc * 16) = *(const u32x4*)(LruW + ((size_t)((dir * 2 + gate) * 8 + h) * 128 + q * 32 + n) * 128 + kc * 8); }
;         const float br = -LOG2E * P.lru_ba[(dir * 8 + h) * 128 + chl], bi = -LOG2E * P.lru_bx[(dir * 8 + h) * 128 + chl];
;         const float lam = P.lru_lambda[dir * 1024 + ch];
;         const float cl = -8.0f * LOG2E * log1pf(__expf(-lam));
;         float carry = 0.f;
;         LruTile cur = lru_tile(Z, ZC, b, h, dir, 0);
;         u32x4 rows[11];
;         constexpr int NIN = dir == 0 ? 2 : 4;
;         u32x4 inr[NIN];
;         lru_load_rows(rows, cur, tr, cgp);
;     ...
;         LDS_BARRIER();
;         if (dir == 0) {
; #pragma unroll
;             for (int i = 0; i < 4; ++i) { const int id = tid + i * NTHREADS; *(u32x4*)(Hg + (size_t)(t0_prev + (id >> 3)) * DM + (id & 7) * 4) = *(const LAS u32x4*)(TOUT + (id >> 3) * IO_WP + (id & 7) * 16); }
.Lpp_f_noy:
	s_waitcnt lgkmcnt(0)
	s_barrier
	v_add_u32_e32 v0, v129, v149
	ds_read_b128 v[0:3], v0
	v_add_u32_e32 v4, s97, v148
	v_ashrrev_i32_e32 v5, 31, v4
	v_lshlrev_b64 v[4:5], 12, v[4:5]
	v_lshl_add_u64 v[8:9], v[130:131], 0, v[4:5]
	v_add_u32_e32 v4, v129, v146
	ds_read_b128 v[4:7], v4
	s_waitcnt lgkmcnt(1)
	global_store_dwordx4 v[8:9], v[0:3], off
	v_cmp_gt_i32_e32 vcc, 64, v128
	s_nop 0
	v_add_u32_e32 v0, s97, v145
	v_ashrrev_i32_e32 v1, 31, v0
	v_lshlrev_b64 v[0:1], 12, v[0:1]
	v_lshl_add_u64 v[0:1], v[130:131], 0, v[0:1]
	s_waitcnt lgkmcnt(0)
	global_store_dwordx4 v[0:1], v[4:7], off
	v_add_u32_e32 v0, v129, v144
	ds_read_b128 v[0:3], v0
	v_add_u32_e32 v4, s97, v143
	v_ashrrev_i32_e32 v5, 31, v4
	v_lshlrev_b64 v[4:5], 12, v[4:5]
	v_lshl_add_u64 v[8:9], v[130:131], 0, v[4:5]
	v_add_u32_e32 v4, v129, v142
	ds_read_b128 v[4:7], v4
	s_waitcnt lgkmcnt(1)
	global_store_dwordx4 v[8:9], v[0:3], off
	s_nop 1
	v_add_u32_e32 v0, s97, v141
	v_ashrrev_i32_e32 v1, 31, v0
	v_lshlrev_b64 v[0:1], 12, v[0:1]
	v_lshl_add_u64 v[0:1], v[130:131], 0, v[0:1]
	s_waitcnt lgkmcnt(0)
	global_store_dwordx4 v[0:1], v[4:7], off
	s_waitcnt lgkmcnt(0)
	s_add_u32 s42, s22, 0x1b00000
	s_addc_u32 s43, s23, 0
	v_mov_b32_e32 v32, v167
	s_barrier
	s_or_b32 s0, s26, 16
	v_and_b32_e32 v15, 31, v32
	v_or_b32_e32 v17, s28, v15
	v_add_u32_e32 v13, 0x200, v32
	v_or_b32_e32 v8, s27, v17
	v_ashrrev_i32_e32 v11, 9, v32
	v_ashrrev_i32_e32 v14, 9, v13
	v_lshlrev_b32_e32 v8, 2, v8
	v_mov_b32_e32 v9, v65
	v_lshl_add_u32 v2, v11, 3, s0
	v_lshl_add_u32 v6, v14, 3, s0
	v_lshl_add_u64 v[8:9], s[64:65], 0, v[8:9]
	s_movk_i32 s0, 0x1000
	v_add_co_u32_e32 v8, vcc, s0, v8
	v_and_b32_e32 v12, 15, v32
	s_nop 0
	v_addc_co_u32_e32 v9, vcc, 0, v9, vcc
	global_load_dword v16, v[8:9], off
	v_bfe_u32 v10, v32, 4, 5
	v_lshlrev_b32_e32 v64, 4, v12
	v_ashrrev_i32_e32 v3, 31, v2
	v_ashrrev_i32_e32 v7, 31, v6
	v_or_b32_e32 v4, s28, v10
	v_lshl_add_u64 v[0:1], s[38:39], 0, v[64:65]
	v_lshlrev_b64 v[2:3], 15, v[2:3]
	v_lshlrev_b64 v[6:7], 15, v[6:7]
	v_lshlrev_b32_e32 v4, 8, v4
	v_mov_b32_e32 v5, v65
	v_lshl_add_u64 v[2:3], v[0:1], 0, v[2:3]
	v_lshl_add_u64 v[0:1], v[0:1], 0, v[6:7]
	v_lshl_add_u64 v[2:3], v[2:3], 0, v[4:5]
	v_lshl_add_u64 v[4:5], v[0:1], 0, v[4:5]
	global_load_dwordx4 v[0:3], v[2:3], off
	s_nop 0
	global_load_dwordx4 v[4:7], v[4:5], off
	v_lshrrev_b32_e32 v8, 1, v32
	v_lshlrev_b32_e32 v9, 2, v32
	v_and_b32_e32 v20, 12, v8
	v_lshl_or_b32 v11, v11, 5, v10
	v_add_u32_e32 v8, s88, v64
	v_lshl_or_b32 v14, v14, 5, v10
	v_mad_u64_u32 v[10:11], s[6:7], v11, s89, v[8:9]
	s_or_b32 s8, s26, 8
	v_and_or_b32 v20, v9, 16, v20
	v_lshlrev_b32_e32 v21, 2, v17
	v_mad_u64_u32 v[8:9], s[6:7], v14, s89, v[8:9]
	v_lshl_or_b32 v9, s8, 9, v21
	global_load_dword v14, v9, s[58:59]
	s_nop 0
	global_load_dword v9, v9, s[62:63]
	s_mov_b32 s80, 0x3f2aaaab
	s_mov_b32 s81, 0x3f317218
	s_mov_b32 s91, 0x7f800000
	s_mov_b32 s92, 0x33800000
	v_ashrrev_i32_e32 v33, 4, v32
	v_lshlrev_b32_e32 v34, 3, v12
	v_readfirstlane_b32 s4, v32
	s_lshl_b64 s[0:1], s[78:79], 11
	s_lshl_b32 s5, s8, 14
	s_ashr_i32 s6, s4, 6
	s_add_u32 s26, s0, s5
	s_addc_u32 s27, s1, 0
	s_lshl_b32 s0, s28, 1
	v_readlane_b32 s1, v255, 10
	v_and_b32_e32 v19, 3, v32
	s_add_u32 s0, s1, s0
	v_bfe_u32 v18, v32, 5, 1
	v_add_u32_e32 v44, 0, v64
	v_lshlrev_b32_e32 v64, 4, v19
	s_addc_u32 s1, s3, 0
	v_lshl_add_u64 v[136:137], s[0:1], 0, v[64:65]
	s_lshl_b32 s0, s6, 5
	v_lshlrev_b32_e32 v46, 4, v18
	v_or_b32_e32 v37, s0, v46
	v_add_u32_e32 v158, s86, v64
	v_or_b32_e32 v64, 4, v37
	s_movk_i32 s93, 0x880
	v_ashrrev_i32_e32 v36, 3, v32
	v_ashrrev_i32_e32 v38, 3, v13
	v_ashrrev_i32_e32 v140, 2, v32
	v_sub_u32_e32 v39, 0xff, v37
	v_sub_u32_e32 v64, 0xff, v64
	v_lshl_add_u32 v160, v33, 3, -1
	v_mul_lo_u32 v52, v33, s93
	v_lshl_or_b32 v110, v33, 13, v34
	v_mov_b32_e32 v111, v65
	v_lshlrev_b64 v[110:111], 1, v[110:111]
	v_lshl_add_u64 v[108:109], s[48:49], 0, v[110:111]
	global_load_dwordx4 v[68:71], v[108:109], off offset:-2048
	global_load_dwordx4 v[72:75], v[108:109], off
	global_load_dwordx4 v[76:79], v[108:109], off offset:2048
	v_lshl_add_u64 v[108:109], s[50:51], 0, v[110:111]
	global_load_dwordx4 v[80:83], v[108:109], off
	v_lshl_add_u64 v[108:109], s[56:57], 0, v[110:111]
	global_load_dwordx4 v[84:87], v[108:109], off
	v_lshl_add_u64 v[108:109], s[60:61], 0, v[110:111]
	global_load_dwordx4 v[88:91], v[108:109], off
	v_lshl_add_u64 v[108:109], s[66:67], 0, v[110:111]
	global_load_dwordx4 v[92:95], v[108:109], off
	v_lshl_add_u64 v[108:109], s[70:71], 0, v[110:111]
	global_load_dwordx4 v[96:99], v[108:109], off
	v_lshl_add_u64 v[108:109], s[72:73], 0, v[110:111]
	global_load_dwordx4 v[100:103], v[108:109], off
	v_lshl_add_u64 v[108:109], s[74:75], 0, v[110:111]
	global_load_dwordx4 v[104:107], v[108:109], off
	v_lshl_add_u64 v[108:109], s[76:77], 0, v[110:111]
	global_load_dwordx4 v[108:111], v[108:109], off
	s_waitcnt vmcnt(14)
	ds_write_b128 v10, v[0:3]
	s_waitcnt vmcnt(13)
; #define LAS __attribute__((address_space(3)))
; __device__ __forceinline__ int opaque_tid() { int t = threadIdx.x; asm volatile("" : "+v"(t)); return t; }
; template <int dir>
; __device__ __forceinline__ void lru_pass(LAS unsigned char* lds, const Params& P, int b, int h, int q, bool dry) {
;     const int tid = opaque_tid(), lane = tid & 63, wid = __builtin_amdgcn_readfirstlane(tid >> 6), g = lane >> 5, nl = lane & 31;
;     const int chl = q * 32 + nl, ch = h * 128 + chl;
;     LAS unsigned char* XC = lds;
;     LAS float* AGG = (LAS float*)(lds + 256 * XC_PITCH);
;     LAS unsigned char* WB = lds + 256 * XC_PITCH + 2048;
;     LAS float* CWL = (LAS float*)(lds + 256 * XC_PITCH + 2048 + 64 * XC_PITCH);
;     LAS unsigned char* TIN = lds + LRU_IO_OFF;
;     LAS unsigned char* TOUT = lds + LRU_IO_OFF + 256 * (dir == 0 ? IO_NP : IO_WP);
;     bf16_t* Z = (bf16_t*)(P.ws + WS_Z); const bf16_t* ZC = (const bf16_t*)(P.ws + WS_ZC); unsigned* HFW = (unsigned*)(P.ws + WS_HF);
;     const bf16_t* LruW = (const bf16_t*)(P.ws + WS_LRUW);
;     const int cgp = tid & 15, tr = tid >> 4;
;     const int s_i = 16 * ((nl >> 2) & 1) + ((nl >> 3) << 2) + (nl & 3);
;     const bf16_t* Zg = Z + ZSLAB(8 + h, (size_t)b * SEQ) + q * 32;
;     unsigned* Hg = HFW + (size_t)b * SEQ * DM + h * 128 + q * 32;
;     ...
;         const float br = -LOG2E * P.lru_ba[(dir * 8 + h) * 128 + chl], bi = -LOG2E * P.lru_bx[(dir * 8 + h) * 128 + chl];
;         const float lam = P.lru_lambda[dir * 1024 + ch];
;         const float cl = -8.0f * LOG2E * log1pf(__expf(-lam));
	ds_write_b128 v8, v[4:7]
	v_mul_f32_e32 v11, 0xbfb8aa3b, v16
	v_exp_f32_e32 v11, v11
	v_mul_lo_u32 v57, v39, s89
	v_mul_lo_u32 v58, v39, s30
	v_mul_lo_u32 v114, v64, s89
	v_add_f32_e32 v2, 1.0, v11
	v_add_f32_e32 v3, -1.0, v2
	v_frexp_mant_f32_e32 v4, v2
	v_cvt_f64_f32_e32 v[0:1], v2
	v_sub_f32_e32 v5, v3, v2
	v_frexp_exp_i32_f64_e32 v0, v[0:1]
	v_cmp_gt_f32_e32 vcc, s80, v4
	v_sub_f32_e32 v3, v11, v3
	v_add_f32_e32 v1, 1.0, v5
	v_subbrev_co_u32_e32 v0, vcc, 0, v0, vcc
	v_add_f32_e32 v1, v3, v1
	v_sub_u32_e32 v3, 0, v0
	v_ldexp_f32 v2, v2, v3
	v_ldexp_f32 v1, v1, v3
	v_add_f32_e32 v3, -1.0, v2
	v_add_f32_e32 v4, 1.0, v2
	v_add_f32_e32 v5, 1.0, v3
	v_add_f32_e32 v6, -1.0, v4
	v_sub_f32_e32 v5, v2, v5
	v_sub_f32_e32 v2, v2, v6
	v_add_f32_e32 v5, v1, v5
	v_add_f32_e32 v1, v1, v2
	v_add_f32_e32 v7, v4, v1
	v_rcp_f32_e32 v8, v7
	v_add_f32_e32 v2, v3, v5
	v_sub_f32_e32 v4, v7, v4
	v_sub_f32_e32 v3, v2, v3
	v_sub_f32_e32 v1, v1, v4
	v_mul_f32_e32 v4, v2, v8
	v_sub_f32_e32 v3, v5, v3
	v_mul_f32_e32 v5, v7, v4
	v_fma_f32 v10, v4, v7, -v5
	v_fmac_f32_e32 v10, v4, v1
	v_add_f32_e32 v16, v5, v10
	v_sub_f32_e32 v21, v2, v16
	v_sub_f32_e32 v2, v2, v21
	v_sub_f32_e32 v5, v16, v5
	v_sub_f32_e32 v2, v2, v16
	v_sub_f32_e32 v5, v5, v10
	v_add_f32_e32 v2, v3, v2
	v_add_f32_e32 v2, v5, v2
	v_add_f32_e32 v3, v21, v2
	v_mul_f32_e32 v5, v8, v3
	v_sub_f32_e32 v10, v21, v3
	v_mul_f32_e32 v16, v7, v5
	v_add_f32_e32 v2, v2, v10
	v_add_f32_e32 v10, v4, v5
	v_fma_f32 v7, v5, v7, -v16
	v_sub_f32_e32 v4, v10, v4
	v_fmac_f32_e32 v7, v5, v1
	v_sub_f32_e32 v1, v5, v4
	v_add_f32_e32 v4, v16, v7
	v_sub_f32_e32 v5, v4, v16
	v_sub_f32_e32 v16, v3, v4
	v_sub_f32_e32 v3, v3, v16
	v_sub_f32_e32 v3, v3, v4
	v_cvt_f32_i32_e32 v0, v0
	v_sub_f32_e32 v5, v5, v7
	v_add_f32_e32 v2, v2, v3
	v_add_f32_e32 v2, v5, v2
	v_add_f32_e32 v2, v16, v2
	v_mul_f32_e32 v2, v8, v2
	v_mul_f32_e32 v6, 0x3f317218, v0
	v_add_f32_e32 v1, v1, v2
	v_add_f32_e32 v2, v10, v1
	v_fma_f32 v5, v0, s81, -v6
	v_fmac_f32_e32 v5, 0xb102e308, v0
	v_sub_f32_e32 v0, v2, v10
	v_mul_f32_e32 v3, v2, v2
	v_sub_f32_e32 v0, v1, v0
	v_add_f32_e32 v1, v6, v5
	v_fmamk_f32 v4, v3, 0x3e9b6dac, v200
	v_sub_f32_e32 v6, v1, v6
	v_fmaak_f32 v4, v3, v4, 0x3f2aaada
	v_sub_f32_e32 v5, v5, v6
	v_ldexp_f32 v6, v2, 1
	v_mul_f32_e32 v2, v2, v3
	v_mul_f32_e32 v2, v2, v4
	v_add_f32_e32 v3, v6, v2
	v_sub_f32_e32 v4, v3, v6
	v_ldexp_f32 v0, v0, 1
	v_sub_f32_e32 v2, v2, v4
	v_add_f32_e32 v0, v0, v2
	v_add_f32_e32 v2, v3, v0
	v_sub_f32_e32 v3, v2, v3
	v_sub_f32_e32 v0, v0, v3
	v_add_f32_e32 v3, v1, v2
	v_sub_f32_e32 v4, v3, v1
	v_sub_f32_e32 v6, v3, v4
	v_sub_f32_e32 v1, v1, v6
	v_sub_f32_e32 v2, v2, v4
	v_add_f32_e32 v1, v2, v1
	v_add_f32_e32 v2, v5, v0
	v_sub_f32_e32 v4, v2, v5
	v_add_f32_e32 v1, v2, v1
	v_sub_f32_e32 v6, v2, v4
	v_add_f32_e32 v2, v3, v1
	v_sub_f32_e32 v5, v5, v6
	v_sub_f32_e32 v0, v0, v4
	v_sub_f32_e32 v3, v2, v3
	v_add_f32_e32 v0, v0, v5
	v_sub_f32_e32 v1, v1, v3
	v_add_f32_e32 v0, v0, v1
	v_add_f32_e32 v0, v2, v0
	v_cmp_neq_f32_e32 vcc, s91, v11
	v_mov_b32_e32 v1, v65
	v_mul_lo_u32 v115, v64, s30
	v_cndmask_b32_e32 v0, v201, v0, vcc
	v_cmp_ngt_f32_e32 vcc, -1.0, v11
	v_mul_lo_u32 v206, v39, s87
	v_mul_lo_u32 v210, v64, s87
	v_cndmask_b32_e32 v0, v202, v0, vcc
	v_cmp_neq_f32_e32 vcc, -1.0, v11
	v_ashrrev_i32_e32 v39, 31, v38
	v_sub_u32_e32 v41, 0xfe, v37
	v_cndmask_b32_e32 v0, v203, v0, vcc
	v_cmp_lt_f32_e64 vcc, |v11|, s92
	v_mul_lo_u32 v59, v41, s89
	v_mul_lo_u32 v60, v41, s30
	v_cndmask_b32_e32 v6, v0, v11, vcc
	v_lshlrev_b32_e32 v2, 4, v32
	v_and_b32_e32 v2, 0x70, v2
	v_lshlrev_b32_e32 v1, 2, v15
	v_add_u32_e32 v45, s95, v2
	v_or3_b32 v2, v19, v20, s0
	s_and_b32 s0, s4, 0x3fffffc0
	v_add_u32_e32 v161, s94, v1
	s_cmp_eq_u32 s6, 7
	v_lshl_add_u32 v254, s0, 2, v161
	s_cselect_b64 s[0:1], -1, 0
	s_cmp_eq_u32 s6, 6
	s_cselect_b64 s[16:17], -1, 0
	s_cmp_eq_u32 s6, 5
	s_cselect_b64 s[4:5], -1, 0
	s_cmp_eq_u32 s6, 4
	s_cselect_b64 s[8:9], -1, 0
	s_cmp_eq_u32 s6, 3
	s_cselect_b64 s[10:11], -1, 0
	s_cmp_eq_u32 s6, 2
	s_cselect_b64 s[12:13], -1, 0
	s_cmp_eq_u32 s6, 1
	s_cselect_b64 s[14:15], -1, 0
	s_lshl_b32 s6, s25, 7
	s_and_b32 s6, s6, 0xe00
	s_lshl_b32 s7, s29, 7
	s_or_b32 s6, s7, s6
	s_add_u32 s6, s6, s44
	v_add_u32_e32 v50, s95, v1
	v_add_u32_e32 v1, 0x400, v32
	s_addc_u32 s7, 0, s45
	v_ashrrev_i32_e32 v40, 3, v1
	v_add_u32_e32 v1, 0x600, v32
	v_and_b32_e32 v32, 7, v32
	s_add_u32 s18, s84, s46
	v_lshlrev_b32_e32 v64, 4, v32
	v_lshl_or_b32 v32, v33, 10, v34
	v_mov_b32_e32 v33, v65
	s_addc_u32 s19, s85, s47
	v_lshl_add_u64 v[144:145], v[32:33], 1, s[18:19]
	v_lshlrev_b64 v[32:33], 12, v[38:39]
	v_lshl_add_u64 v[32:33], s[6:7], 0, v[32:33]
	v_mul_lo_u32 v207, v41, s87
	v_lshl_add_u64 v[32:33], v[32:33], 0, v[64:65]
	v_ashrrev_i32_e32 v41, 31, v40
	v_or_b32_e32 v43, 2, v37
	v_lshl_add_u64 v[252:253], s[42:43], 0, v[32:33]
	v_lshlrev_b64 v[32:33], 12, v[40:41]
	v_ashrrev_i32_e32 v42, 3, v1
	v_sub_u32_e32 v43, 0xff, v43
	v_or_b32_e32 v63, 3, v37
	v_or_b32_e32 v66, 5, v37
	v_or_b32_e32 v67, 6, v37
	v_or_b32_e32 v120, 7, v37
	v_or_b32_e32 v123, 8, v37
	v_or_b32_e32 v126, 9, v37
	v_or_b32_e32 v129, 10, v37
	v_or_b32_e32 v132, 11, v37
	v_or_b32_e32 v135, 12, v37
	v_or_b32_e32 v142, 13, v37
	v_or_b32_e32 v143, 14, v37
	v_or_b32_e32 v37, 15, v37
	v_lshl_add_u64 v[32:33], s[6:7], 0, v[32:33]
	v_mul_lo_u32 v61, v43, s89
	v_mul_lo_u32 v62, v43, s30
	v_sub_u32_e32 v37, 0xff, v37
	v_mul_lo_u32 v208, v43, s87
	v_lshl_add_u64 v[32:33], v[32:33], 0, v[64:65]
	v_ashrrev_i32_e32 v43, 31, v42
	v_sub_u32_e32 v2, 0xff, v2
	v_mul_lo_u32 v204, v37, s89
	v_mul_lo_u32 v205, v37, s30
	v_mul_lo_u32 v221, v37, s87
	v_ashrrev_i32_e32 v37, 31, v36
	v_lshl_add_u64 v[154:155], s[42:43], 0, v[32:33]
	v_lshlrev_b64 v[32:33], 12, v[42:43]
	v_mul_lo_u32 v2, v2, s89
	v_mul_lo_u32 v53, v36, s30
	v_sub_u32_e32 v63, 0xff, v63
	v_sub_u32_e32 v66, 0xff, v66
	v_sub_u32_e32 v67, 0xff, v67
	v_sub_u32_e32 v120, 0xff, v120
	v_sub_u32_e32 v123, 0xff, v123
	v_sub_u32_e32 v126, 0xff, v126
	v_lshlrev_b64 v[36:37], 12, v[36:37]
	v_lshl_add_u64 v[32:33], s[6:7], 0, v[32:33]
	v_lshlrev_b32_e32 v35, 5, v12
	v_add_u32_e32 v47, 0, v2
	v_mov_b32_e32 v2, s88
	v_lshl_add_u32 v49, v17, 1, 0
	v_lshl_add_u32 v51, v15, 1, s86
	v_mul_lo_u32 v112, v63, s89
	v_mul_lo_u32 v113, v63, s30
	v_mul_lo_u32 v116, v66, s89
	v_mul_lo_u32 v117, v66, s30
	v_mul_lo_u32 v118, v67, s89
	v_mul_lo_u32 v119, v67, s30
	v_mul_lo_u32 v121, v120, s89
	v_mul_lo_u32 v122, v120, s30
	v_mul_lo_u32 v124, v123, s89
	v_mul_lo_u32 v125, v123, s30
	v_mul_lo_u32 v127, v126, s89
	v_mul_lo_u32 v128, v126, s30
	v_sub_u32_e32 v129, 0xff, v129
	v_sub_u32_e32 v132, 0xff, v132
	v_sub_u32_e32 v135, 0xff, v135
	v_sub_u32_e32 v142, 0xff, v142
	v_sub_u32_e32 v143, 0xff, v143
	v_mul_lo_u32 v211, v66, s87
	v_mul_lo_u32 v212, v67, s87
	v_mul_lo_u32 v120, v120, s87
	v_mul_lo_u32 v123, v123, s87
	v_mul_lo_u32 v126, v126, s87
	v_lshl_add_u64 v[36:37], s[6:7], 0, v[36:37]
	v_lshl_add_u64 v[32:33], v[32:33], 0, v[64:65]
	v_mov_b32_e32 v66, v65
	v_mov_b32_e32 v67, v65
	s_waitcnt vmcnt(12)
; template <int dir>
; __device__ __forceinline__ void lru_pass(LAS unsigned char* lds, const Params& P, int b, int h, int q, bool dry) {
;     ...
;         const float br = -LOG2E * P.lru_ba[(dir * 8 + h) * 128 + chl], bi = -LOG2E * P.lru_bx[(dir * 8 + h) * 128 + chl];
;         const float lam = P.lru_lambda[dir * 1024 + ch];
;         const float cl = -8.0f * LOG2E * log1pf(__expf(-lam));
;         float carry = 0.f;
;         LruTile cur = lru_tile(Z, ZC, b, h, dir, 0);
;         u32x4 rows[11];
;         constexpr int NIN = dir == 0 ? 2 : 4;
;         u32x4 inr[NIN];
;         lru_load_rows(rows, cur, tr, cgp);
; #pragma unroll
;         for (int i = 0; i < NIN; ++i) inr[i] = (u32x4){0u, 0u, 0u, 0u};
;         int t0_prev = 0;
;     ...
;             f32x16 zr, zi;
; #pragma unroll
;             for (int v = 0; v < 16; ++v) { zr[v] = br; zi[v] = bi; }
;             const int sbase = 32 * wid + 16 * g;
	v_mul_f32_e32 v0, 0xbfb8aa3b, v14
	s_waitcnt vmcnt(11)
	v_mul_f32_e32 v16, 0xbfb8aa3b, v9
	v_mad_u32_u24 v48, v15, s89, v2
	v_mul_lo_u32 v54, v38, s30
	v_mul_lo_u32 v55, v40, s30
	v_mul_lo_u32 v56, v42, s30
	v_ashrrev_i32_e32 v138, 2, v13
	v_mul_lo_u32 v130, v129, s89
	v_mul_lo_u32 v131, v129, s30
	v_mul_lo_u32 v133, v132, s89
	v_mul_lo_u32 v134, v132, s30
	v_mul_lo_u32 v146, v135, s89
	v_mul_lo_u32 v147, v135, s30
	v_mul_lo_u32 v148, v142, s89
	v_mul_lo_u32 v149, v142, s30
	v_mul_lo_u32 v162, v143, s89
	v_mul_lo_u32 v163, v143, s30
	v_mul_lo_u32 v63, v63, s87
	v_mul_lo_u32 v129, v129, s87
	v_mul_lo_u32 v132, v132, s87
	v_mul_lo_u32 v135, v135, s87
	v_mul_lo_u32 v219, v142, s87
	v_mul_lo_u32 v220, v143, s87
	v_lshl_add_u64 v[36:37], v[36:37], 0, v[64:65]
	v_lshl_add_u64 v[150:151], s[42:43], 0, v[32:33]
	v_mov_b32_e32 v64, v65
	v_add_u32_e32 v32, 0, v35
	v_add_u32_e32 v180, v49, v112
	v_add_u32_e32 v181, v50, v113
	v_add_u32_e32 v182, v49, v114
	v_add_u32_e32 v183, v50, v115
	v_add_u32_e32 v184, v49, v116
	v_add_u32_e32 v185, v50, v117
	v_add_u32_e32 v186, v49, v118
	v_add_u32_e32 v187, v50, v119
	v_add_u32_e32 v188, v49, v121
	v_add_u32_e32 v189, v50, v122
	v_add_u32_e32 v190, v49, v124
	v_add_u32_e32 v191, v50, v125
	v_add_u32_e32 v192, v49, v127
	v_add_u32_e32 v213, v51, v120
	v_add_u32_e32 v214, v51, v123
	v_add_u32_e32 v215, v51, v126
	v_mov_b64_e32 v[114:115], v[66:67]
	v_mov_b64_e32 v[118:119], v[66:67]
	v_mov_b64_e32 v[122:123], v[66:67]
	v_mov_b64_e32 v[126:127], v[66:67]
	s_mov_b32 s78, 0
	v_mov_b32_e32 v156, 0xff800000
	v_mul_f32_e32 v159, 0xc138aa3b, v6
	v_cmp_eq_u32_e32 vcc, 0, v18
	v_mul_lo_u32 v164, v140, s87
	v_ashrrev_i32_e32 v141, 31, v140
	v_mul_lo_u32 v152, v138, s87
	v_ashrrev_i32_e32 v139, 31, v138
	v_mov_b32_e32 v1, v0
	v_mov_b32_e32 v2, v0
	v_mov_b32_e32 v3, v0
	v_mov_b32_e32 v4, v0
	v_mov_b32_e32 v5, v0
	v_mov_b32_e32 v6, v0
	v_mov_b32_e32 v7, v0
	v_mov_b32_e32 v8, v0
	v_mov_b32_e32 v9, v0
	v_mov_b32_e32 v10, v0
	v_mov_b32_e32 v11, v0
	v_mov_b32_e32 v12, v0
	v_mov_b32_e32 v13, v0
	v_mov_b32_e32 v14, v0
	v_mov_b32_e32 v15, v0
	v_mov_b32_e32 v17, v16
	v_mov_b32_e32 v18, v16
	v_mov_b32_e32 v19, v16
	v_mov_b32_e32 v20, v16
	v_mov_b32_e32 v21, v16
	v_mov_b32_e32 v22, v16
	v_mov_b32_e32 v23, v16
	v_mov_b32_e32 v24, v16
	v_mov_b32_e32 v25, v16
	v_mov_b32_e32 v26, v16
	v_mov_b32_e32 v27, v16
	v_mov_b32_e32 v28, v16
	v_mov_b32_e32 v29, v16
	v_mov_b32_e32 v30, v16
	v_mov_b32_e32 v31, v16
	v_lshl_add_u64 v[142:143], s[42:43], 0, v[36:37]
	s_movk_i32 s28, 0x100
	v_mov_b32_e32 v222, 0
	s_mov_b64 s[44:45], 0
	s_movk_i32 s25, 0x700
	v_add_u32_e32 v165, 0x15c00, v32
	v_add_u32_e32 v166, v44, v52
	v_add_u32_e32 v168, v45, v53
	v_add_u32_e32 v169, v45, v54
	v_add_u32_e32 v170, v45, v55
	v_add_u32_e32 v171, v45, v56
	v_add_u32_e32 v172, v47, v46
	v_add_u32_e32 v173, v48, v46
	v_add_u32_e32 v174, v49, v57
	v_add_u32_e32 v175, v50, v58
	v_add_u32_e32 v176, v49, v59
	v_add_u32_e32 v177, v50, v60
	v_add_u32_e32 v178, v49, v61
	v_add_u32_e32 v179, v50, v62
	v_add_u32_e32 v193, v50, v128
	v_add_u32_e32 v194, v49, v130
	v_add_u32_e32 v195, v50, v131
	v_add_u32_e32 v196, v49, v133
	v_add_u32_e32 v197, v50, v134
	v_add_u32_e32 v198, v49, v146
	v_add_u32_e32 v199, v50, v147
	v_add_u32_e32 v200, v49, v148
	v_add_u32_e32 v201, v50, v149
	v_add_u32_e32 v202, v49, v162
	v_add_u32_e32 v203, v50, v163
	v_add_u32_e32 v204, v49, v204
	v_add_u32_e32 v205, v50, v205
	v_add_u32_e32 v206, v51, v206
	v_add_u32_e32 v207, v51, v207
	v_add_u32_e32 v208, v51, v208
	v_add_u32_e32 v209, v51, v63
	v_add_u32_e32 v210, v51, v210
	v_add_u32_e32 v211, v51, v211
	v_add_u32_e32 v212, v51, v212
	v_add_u32_e32 v216, v51, v129
	v_add_u32_e32 v217, v51, v132
	v_add_u32_e32 v218, v51, v135
	v_add_u32_e32 v219, v51, v219
	v_add_u32_e32 v220, v51, v220
	v_add_u32_e32 v221, v51, v221
	v_mov_b64_e32 v[112:113], v[64:65]
	v_mov_b64_e32 v[116:117], v[64:65]
	v_mov_b64_e32 v[120:121], v[64:65]
	v_mov_b64_e32 v[124:125], v[64:65]
	s_mov_b32 s46, 0
	s_mov_b32 s29, 0
	v_lshrrev_b32_e32 v32, 8, v167
	v_mul_u32_u24_e32 v33, 0x3600, v32
	v_add_u32_e32 v168, v168, v33
	v_add_u32_e32 v169, v169, v33
	v_add_u32_e32 v170, v170, v33
	v_add_u32_e32 v171, v171, v33
	v_add_u32_e32 v169, 0xffffee00, v169
	v_add_u32_e32 v170, 0xffffdc00, v170
	v_add_u32_e32 v171, 0xffffca00, v171
	v_mul_u32_u24_e32 v66, 0x60000, v32
; template <int dir>
; __device__ __forceinline__ void lru_pass(LAS unsigned char* lds, const Params& P, int b, int h, int q, bool dry) {
;     ...
;         for (int sc = 0; sc < 9; ++sc) {
;             const bool isctx = (sc == 0);
;             const int t0 = cur.t0;
; #pragma unroll
;             for (int j = 0; j < 11; ++j) { if (j != 0 && j < 9) continue;
;                 const int t = t0 + tr * 8 - 1 + j; if (t < 0 || t >= cur.L) rows[j] = (u32x4){0u, 0u, 0u, 0u}; }
	v_mov_b32_e32 v67, 0
	v_lshl_add_u64 v[142:143], v[66:67], 0, v[142:143]
	v_lshl_add_u64 v[252:253], v[66:67], 0, v[252:253]
	v_lshl_add_u64 v[154:155], v[66:67], 0, v[154:155]
	v_lshl_add_u64 v[150:151], v[66:67], 0, v[150:151]
	s_mov_b32 s19, -1
	s_mov_b32 s18, 0xfffe0000
	v_lshl_add_u64 v[252:253], v[252:253], 0, s[18:19]
	s_mov_b32 s18, 0xfffc0000
	v_lshl_add_u64 v[154:155], v[154:155], 0, s[18:19]
	s_mov_b32 s18, 0xfffa0000
	v_lshl_add_u64 v[150:151], v[150:151], 0, s[18:19]
	v_mul_u32_u24_e32 v33, 0x1400, v32
	v_add_u32_e32 v164, v164, v33
	v_add_u32_e32 v152, v152, v33
	v_add_u32_e32 v152, 0xffffec00, v152
	v_lshlrev_b32_e32 v33, 6, v32
	v_add_u32_e32 v140, v140, v33
	v_add_u32_e32 v138, v138, v33
	v_add_u32_e32 v138, 0xffffffc0, v138
	v_lshrrev_b32_e32 v33, 6, v167
	s_nop 1
	v_readfirstlane_b32 s18, v33
	s_lshl_b32 s19, s18, 6
	s_sub_i32 s19, s19, 0xe0
	s_mul_i32 s20, s19, 0x110
	v_add_u32_e32 v172, s20, v172
	v_add_u32_e32 v174, s20, v174
	v_add_u32_e32 v176, s20, v176
	v_add_u32_e32 v178, s20, v178
	v_add_u32_e32 v180, s20, v180
	v_add_u32_e32 v182, s20, v182
	v_add_u32_e32 v184, s20, v184
	v_add_u32_e32 v186, s20, v186
	v_add_u32_e32 v188, s20, v188
	v_add_u32_e32 v190, s20, v190
	v_add_u32_e32 v192, s20, v192
	v_add_u32_e32 v194, s20, v194
	v_add_u32_e32 v196, s20, v196
	v_add_u32_e32 v198, s20, v198
	v_add_u32_e32 v200, s20, v200
	v_add_u32_e32 v202, s20, v202
	v_add_u32_e32 v204, s20, v204
	s_mul_i32 s20, s19, 0x90
	v_add_u32_e32 v175, s20, v175
	v_add_u32_e32 v177, s20, v177
	v_add_u32_e32 v179, s20, v179
	v_add_u32_e32 v181, s20, v181
	v_add_u32_e32 v183, s20, v183
	v_add_u32_e32 v185, s20, v185
	v_add_u32_e32 v187, s20, v187
	v_add_u32_e32 v189, s20, v189
	v_add_u32_e32 v191, s20, v191
	v_add_u32_e32 v193, s20, v193
	v_add_u32_e32 v195, s20, v195
	v_add_u32_e32 v197, s20, v197
	v_add_u32_e32 v199, s20, v199
	v_add_u32_e32 v201, s20, v201
	v_add_u32_e32 v203, s20, v203
	v_add_u32_e32 v205, s20, v205
	s_mul_i32 s20, s19, 0x50
	v_add_u32_e32 v206, s20, v206
	v_add_u32_e32 v207, s20, v207
	v_add_u32_e32 v208, s20, v208
	v_add_u32_e32 v209, s20, v209
	v_add_u32_e32 v210, s20, v210
	v_add_u32_e32 v211, s20, v211
	v_add_u32_e32 v212, s20, v212
	v_add_u32_e32 v213, s20, v213
	v_add_u32_e32 v214, s20, v214
	v_add_u32_e32 v215, s20, v215
	v_add_u32_e32 v216, s20, v216
	v_add_u32_e32 v217, s20, v217
	v_add_u32_e32 v218, s20, v218
	v_add_u32_e32 v219, s20, v219
	v_add_u32_e32 v220, s20, v220
	v_add_u32_e32 v221, s20, v221
	s_lshl_b32 s20, s18, 1
	s_sub_i32 s20, 7, s20
	s_lshl_b32 s20, s20, 8
	v_add_u32_e32 v254, s20, v254
	s_sub_i32 s18, 7, s18
	s_lshr_b32 s101, s18, 2
	s_or_b32 s19, s18, 4
	s_cmp_eq_u32 s19, 7
	s_cselect_b64 s[0:1], -1, 0
	s_cmp_eq_u32 s19, 6
	s_cselect_b64 s[16:17], -1, 0
	s_cmp_eq_u32 s19, 5
	s_cselect_b64 s[4:5], -1, 0
	s_cmp_eq_u32 s19, 4
	s_cselect_b64 s[8:9], -1, 0
	s_cmp_eq_u32 s19, 3
	s_cselect_b64 s[10:11], -1, 0
	s_cmp_eq_u32 s19, 2
	s_cselect_b64 s[12:13], -1, 0
	s_cmp_eq_u32 s19, 1
	s_cselect_b64 s[14:15], -1, 0
	s_mov_b32 s98, 0
	s_cmp_eq_u32 s101, 0
	s_cselect_b32 s99, 0x14400, 0
	s_cselect_b32 s100, 0, 0x400
	v_add_u32_e32 v33, 0x14000, v254
	v_mov_b32_e32 v66, 1.0
	v_mov_b32_e32 v67, 0
	ds_write2_b32 v33, v66, v67 offset1:32
	s_cmp_eq_u32 s101, 0
	s_cbranch_scc1 .Lpp_b_nox
	s_waitcnt lgkmcnt(0)
	s_barrier
.Lpp_b_nox:
.LBB0_306:
	s_cmp_lg_u32 s29, 0
	s_cselect_b32 s90, 1, 0
	s_add_i32 s18, s29, 0x102
	s_cmp_le_i32 s18, s28
	s_cselect_b32 s18, 1, 0
	s_and_b32 s90, s90, s18
	s_cmp_lg_u32 s90, 0
	s_cbranch_scc1 .Lmsk_b_in
	v_add_u32_e32 v32, s29, v160
	v_cmp_lt_i32_e64 s[18:19], -1, v32
	v_cmp_gt_i32_e64 s[20:21], s28, v32
	s_and_b64 s[18:19], s[18:19], s[20:21]
	v_add_u32_e32 v33, 9, v32
	s_waitcnt vmcnt(10)
	v_cndmask_b32_e64 v71, 0, v71, s[18:19]
	v_cndmask_b32_e64 v70, 0, v70, s[18:19]
	v_cndmask_b32_e64 v69, 0, v69, s[18:19]
	v_cndmask_b32_e64 v68, 0, v68, s[18:19]
	v_cmp_lt_i32_e64 s[18:19], -10, v32
	v_cmp_gt_i32_e64 s[20:21], s28, v33
	s_and_b64 s[18:19], s[18:19], s[20:21]
	v_add_u32_e32 v33, 10, v32
	s_waitcnt vmcnt(1)
	v_cndmask_b32_e64 v107, 0, v107, s[18:19]
	v_cndmask_b32_e64 v106, 0, v106, s[18:19]
	v_cndmask_b32_e64 v105, 0, v105, s[18:19]
	v_cndmask_b32_e64 v104, 0, v104, s[18:19]
	v_cmp_lt_i32_e64 s[18:19], -11, v32
	v_cmp_gt_i32_e64 s[20:21], s28, v33
	s_branch .Lmsk_b_j

; #define LAS __attribute__((address_space(3)))
; __device__ __forceinline__ unsigned cvt_pk_bf16(float lo, float hi) { unsigned r; asm volatile("v_cvt_pk_bf16_f32 %0, %1, %2" : "=v"(r) : "v"(lo), "v"(hi)); return r; }
; __device__ __forceinline__ float bf_lo(unsigned u) { return __uint_as_float(u << 16); }
; __device__ __forceinline__ float bf_hi(unsigned u) { return __uint_as_float(u & 0xffff0000u); }
; template <int dir>
; __device__ __forceinline__ void lru_pass(LAS unsigned char* lds, const Params& P, int b, int h, int q, bool dry) {
;     ...
;             f32x2 cw2[4][4], cb2[4];
; #pragma unroll
;             for (int k = 0; k < 5; ++k) { const f32x4 a = *(const LAS f32x4*)(CWL + k * 128 + cgp * 8), c2 = *(const LAS f32x4*)(CWL + k * 128 + cgp * 8 + 4);
;                 if (k < 4) { cw2[k][0] = (f32x2){a[0], a[1]}; cw2[k][1] = (f32x2){a[2], a[3]}; cw2[k][2] = (f32x2){c2[0], c2[1]}; cw2[k][3] = (f32x2){c2[2], c2[3]}; }
;                 else { cb2[0] = (f32x2){a[0], a[1]}; cb2[1] = (f32x2){a[2], a[3]}; cb2[2] = (f32x2){c2[0], c2[1]}; cb2[3] = (f32x2){c2[2], c2[3]}; } }
; #pragma unroll
;             for (int j = 0; j < 8; ++j) {
;                 f32x2 o0 = cb2[0], o1 = cb2[1], o2 = cb2[2], o3 = cb2[3];
; #pragma unroll
;                 for (int k = 0; k < 4; ++k) { const u32x4 rr = rows[j + k];
;                     o0 = cw2[k][0] * (f32x2){bf_lo(rr.x), bf_hi(rr.x)} + o0; o1 = cw2[k][1] * (f32x2){bf_lo(rr.y), bf_hi(rr.y)} + o1;
;                     o2 = cw2[k][2] * (f32x2){bf_lo(rr.z), bf_hi(rr.z)} + o2; o3 = cw2[k][3] * (f32x2){bf_lo(rr.w), bf_hi(rr.w)} + o3; }
;                 u32x4 w; w.x = cvt_pk_bf16(o0[0], o0[1]); w.y = cvt_pk_bf16(o1[0], o1[1]); w.z = cvt_pk_bf16(o2[0], o2[1]); w.w = cvt_pk_bf16(o3[0], o3[1]);
;                 *(LAS u32x4*)(XC + (tr * 8 + j) * XC_PITCH + cgp * 16) = w;
;             }
.Lmsk_b_j:
	ds_read_b128 v[60:63], v165
	ds_read_b128 v[52:55], v165 offset:16
	ds_read_b128 v[44:47], v165 offset:528
	ds_read_b128 v[56:59], v165 offset:512
	ds_read_b128 v[40:43], v165 offset:1040
	ds_read_b128 v[48:51], v165 offset:1024
	ds_read_b128 v[128:131], v165 offset:2064
	ds_read_b128 v[132:135], v165 offset:2048
	ds_read_b128 v[32:35], v165 offset:1552
	ds_read_b128 v[36:39], v165 offset:1536
	v_lshlrev_b32_e32 v66, 16, v68
	v_and_b32_e32 v67, 0xffff0000, v68
	v_lshlrev_b32_e32 v148, 16, v70
	v_and_b32_e32 v149, 0xffff0000, v70
	s_waitcnt lgkmcnt(2)
	v_pk_fma_f32 v[66:67], v[60:61], v[66:67], v[132:133]
	v_lshlrev_b32_e32 v146, 16, v69
	v_and_b32_e32 v147, 0xffff0000, v69
	v_pk_fma_f32 v[148:149], v[52:53], v[148:149], v[128:129]
	v_lshlrev_b32_e32 v224, 16, v71
	v_and_b32_e32 v225, 0xffff0000, v71
	v_lshlrev_b32_e32 v228, 16, v72
	v_and_b32_e32 v229, 0xffff0000, v72
	v_lshlrev_b32_e32 v232, 16, v74
	v_and_b32_e32 v233, 0xffff0000, v74
	v_pk_fma_f32 v[146:147], v[62:63], v[146:147], v[134:135]
	v_pk_fma_f32 v[224:225], v[54:55], v[224:225], v[130:131]
	v_pk_fma_f32 v[66:67], v[56:57], v[228:229], v[66:67]
	v_lshlrev_b32_e32 v230, 16, v73
	v_and_b32_e32 v231, 0xffff0000, v73
	v_pk_fma_f32 v[148:149], v[44:45], v[232:233], v[148:149]
	v_lshlrev_b32_e32 v234, 16, v75
	v_and_b32_e32 v235, 0xffff0000, v75
	v_lshlrev_b32_e32 v236, 16, v76
	v_and_b32_e32 v237, 0xffff0000, v76
	v_lshlrev_b32_e32 v240, 16, v78
	v_and_b32_e32 v241, 0xffff0000, v78
	v_pk_fma_f32 v[146:147], v[58:59], v[230:231], v[146:147]
	v_pk_fma_f32 v[224:225], v[46:47], v[234:235], v[224:225]
	v_pk_fma_f32 v[66:67], v[48:49], v[236:237], v[66:67]
	v_lshlrev_b32_e32 v238, 16, v77
	v_and_b32_e32 v239, 0xffff0000, v77
	v_pk_fma_f32 v[148:149], v[40:41], v[240:241], v[148:149]
	v_lshlrev_b32_e32 v242, 16, v79
	v_and_b32_e32 v243, 0xffff0000, v79
	v_lshlrev_b32_e32 v244, 16, v80
	v_and_b32_e32 v245, 0xffff0000, v80
	v_lshlrev_b32_e32 v248, 16, v82
	v_and_b32_e32 v249, 0xffff0000, v82
	v_pk_fma_f32 v[146:147], v[50:51], v[238:239], v[146:147]
	v_pk_fma_f32 v[224:225], v[42:43], v[242:243], v[224:225]
	s_waitcnt lgkmcnt(0)
	v_pk_fma_f32 v[66:67], v[36:37], v[244:245], v[66:67]
	v_lshlrev_b32_e32 v246, 16, v81
	v_and_b32_e32 v247, 0xffff0000, v81
	v_pk_fma_f32 v[148:149], v[32:33], v[248:249], v[148:149]
	v_lshlrev_b32_e32 v250, 16, v83
	v_and_b32_e32 v251, 0xffff0000, v83
	v_pk_fma_f32 v[146:147], v[38:39], v[246:247], v[146:147]
	v_pk_fma_f32 v[162:163], v[34:35], v[250:251], v[224:225]
	v_cvt_pk_bf16_f32 v224, v66, v67
	v_cvt_pk_bf16_f32 v225, v146, v147
	v_cvt_pk_bf16_f32 v226, v148, v149
	v_pk_fma_f32 v[66:67], v[60:61], v[228:229], v[132:133]
	v_pk_fma_f32 v[148:149], v[52:53], v[232:233], v[128:129]
	v_pk_fma_f32 v[146:147], v[62:63], v[230:231], v[134:135]
	v_pk_fma_f32 v[66:67], v[56:57], v[236:237], v[66:67]
	v_pk_fma_f32 v[148:149], v[44:45], v[240:241], v[148:149]
	v_pk_fma_f32 v[146:147], v[58:59], v[238:239], v[146:147]
	v_pk_fma_f32 v[66:67], v[48:49], v[244:245], v[66:67]
	v_pk_fma_f32 v[148:149], v[40:41], v[248:249], v[148:149]
	v_lshlrev_b32_e32 v228, 16, v84
	v_and_b32_e32 v229, 0xffff0000, v84
	v_lshlrev_b32_e32 v232, 16, v86
	v_and_b32_e32 v233, 0xffff0000, v86
	v_cvt_pk_bf16_f32 v227, v162, v163
	v_pk_fma_f32 v[162:163], v[54:55], v[234:235], v[130:131]
	v_pk_fma_f32 v[146:147], v[50:51], v[246:247], v[146:147]
	v_pk_fma_f32 v[66:67], v[36:37], v[228:229], v[66:67]
	v_lshlrev_b32_e32 v230, 16, v85
	v_and_b32_e32 v231, 0xffff0000, v85
	v_pk_fma_f32 v[148:149], v[32:33], v[232:233], v[148:149]
	ds_write_b128 v166, v[224:227]
	v_pk_fma_f32 v[162:163], v[46:47], v[242:243], v[162:163]
	v_pk_fma_f32 v[146:147], v[38:39], v[230:231], v[146:147]
	v_cvt_pk_bf16_f32 v224, v66, v67
	v_pk_fma_f32 v[66:67], v[60:61], v[236:237], v[132:133]
	v_cvt_pk_bf16_f32 v225, v146, v147
	v_cvt_pk_bf16_f32 v226, v148, v149
	v_pk_fma_f32 v[148:149], v[52:53], v[240:241], v[128:129]
	v_pk_fma_f32 v[162:163], v[42:43], v[250:251], v[162:163]
	v_lshlrev_b32_e32 v234, 16, v87
	v_and_b32_e32 v235, 0xffff0000, v87
	v_pk_fma_f32 v[146:147], v[62:63], v[238:239], v[134:135]
	v_pk_fma_f32 v[66:67], v[56:57], v[244:245], v[66:67]
	v_pk_fma_f32 v[148:149], v[44:45], v[248:249], v[148:149]
	v_pk_fma_f32 v[162:163], v[34:35], v[234:235], v[162:163]
	v_pk_fma_f32 v[146:147], v[58:59], v[246:247], v[146:147]
	v_pk_fma_f32 v[66:67], v[48:49], v[228:229], v[66:67]
	v_pk_fma_f32 v[148:149], v[40:41], v[232:233], v[148:149]
	v_lshlrev_b32_e32 v236, 16, v88
	v_and_b32_e32 v237, 0xffff0000, v88
	v_lshlrev_b32_e32 v240, 16, v90
	v_and_b32_e32 v241, 0xffff0000, v90
	v_cvt_pk_bf16_f32 v227, v162, v163
	v_pk_fma_f32 v[162:163], v[54:55], v[242:243], v[130:131]
	v_pk_fma_f32 v[146:147], v[50:51], v[230:231], v[146:147]
	v_pk_fma_f32 v[66:67], v[36:37], v[236:237], v[66:67]
	v_lshlrev_b32_e32 v238, 16, v89
	v_and_b32_e32 v239, 0xffff0000, v89
	v_pk_fma_f32 v[148:149], v[32:33], v[240:241], v[148:149]
	ds_write_b128 v166, v[224:227] offset:272
	v_pk_fma_f32 v[162:163], v[46:47], v[250:251], v[162:163]
	v_pk_fma_f32 v[146:147], v[38:39], v[238:239], v[146:147]
	v_cvt_pk_bf16_f32 v224, v66, v67
	v_pk_fma_f32 v[66:67], v[60:61], v[244:245], v[132:133]
	v_cvt_pk_bf16_f32 v225, v146, v147
	v_cvt_pk_bf16_f32 v226, v148, v149
	v_pk_fma_f32 v[148:149], v[52:53], v[248:249], v[128:129]
	v_pk_fma_f32 v[162:163], v[42:43], v[234:235], v[162:163]
	v_lshlrev_b32_e32 v242, 16, v91
	v_and_b32_e32 v243, 0xffff0000, v91
	v_pk_fma_f32 v[146:147], v[62:63], v[246:247], v[134:135]
	v_pk_fma_f32 v[66:67], v[56:57], v[228:229], v[66:67]
	v_pk_fma_f32 v[148:149], v[44:45], v[232:233], v[148:149]
; #define LAS __attribute__((address_space(3)))
; __device__ __forceinline__ unsigned cvt_pk_bf16(float lo, float hi) { unsigned r; asm volatile("v_cvt_pk_bf16_f32 %0, %1, %2" : "=v"(r) : "v"(lo), "v"(hi)); return r; }
; __device__ __forceinline__ float bf_lo(unsigned u) { return __uint_as_float(u << 16); }
; __device__ __forceinline__ float bf_hi(unsigned u) { return __uint_as_float(u & 0xffff0000u); }
; template <int dir>
; __device__ __forceinline__ void lru_pass(LAS unsigned char* lds, const Params& P, int b, int h, int q, bool dry) {
;     ...
;             for (int j = 0; j < 8; ++j) {
;                 f32x2 o0 = cb2[0], o1 = cb2[1], o2 = cb2[2], o3 = cb2[3];
; #pragma unroll
;                 for (int k = 0; k < 4; ++k) { const u32x4 rr = rows[j + k];
;                     o0 = cw2[k][0] * (f32x2){bf_lo(rr.x), bf_hi(rr.x)} + o0; o1 = cw2[k][1] * (f32x2){bf_lo(rr.y), bf_hi(rr.y)} + o1;
;                     o2 = cw2[k][2] * (f32x2){bf_lo(rr.z), bf_hi(rr.z)} + o2; o3 = cw2[k][3] * (f32x2){bf_lo(rr.w), bf_hi(rr.w)} + o3; }
;                 u32x4 w; w.x = cvt_pk_bf16(o0[0], o0[1]); w.y = cvt_pk_bf16(o1[0], o1[1]); w.z = cvt_pk_bf16(o2[0], o2[1]); w.w = cvt_pk_bf16(o3[0], o3[1]);
;                 *(LAS u32x4*)(XC + (tr * 8 + j) * XC_PITCH + cgp * 16) = w;
;             }
	v_pk_fma_f32 v[162:163], v[34:35], v[242:243], v[162:163]
	v_pk_fma_f32 v[146:147], v[58:59], v[230:231], v[146:147]
	v_pk_fma_f32 v[66:67], v[48:49], v[236:237], v[66:67]
	v_pk_fma_f32 v[148:149], v[40:41], v[240:241], v[148:149]
	v_lshlrev_b32_e32 v244, 16, v92
	v_and_b32_e32 v245, 0xffff0000, v92
	v_lshlrev_b32_e32 v248, 16, v94
	v_and_b32_e32 v249, 0xffff0000, v94
	v_cvt_pk_bf16_f32 v227, v162, v163
	v_pk_fma_f32 v[162:163], v[54:55], v[250:251], v[130:131]
	v_pk_fma_f32 v[146:147], v[50:51], v[238:239], v[146:147]
	v_pk_fma_f32 v[66:67], v[36:37], v[244:245], v[66:67]
	v_lshlrev_b32_e32 v246, 16, v93
	v_and_b32_e32 v247, 0xffff0000, v93
	v_pk_fma_f32 v[148:149], v[32:33], v[248:249], v[148:149]
	ds_write_b128 v166, v[224:227] offset:544
	v_pk_fma_f32 v[162:163], v[46:47], v[234:235], v[162:163]
	v_pk_fma_f32 v[146:147], v[38:39], v[246:247], v[146:147]
	v_cvt_pk_bf16_f32 v224, v66, v67
	v_pk_fma_f32 v[66:67], v[60:61], v[228:229], v[132:133]
	v_cvt_pk_bf16_f32 v225, v146, v147
	v_cvt_pk_bf16_f32 v226, v148, v149
	v_pk_fma_f32 v[148:149], v[52:53], v[232:233], v[128:129]
	v_pk_fma_f32 v[162:163], v[42:43], v[242:243], v[162:163]
	v_lshlrev_b32_e32 v250, 16, v95
	v_and_b32_e32 v251, 0xffff0000, v95
	v_pk_fma_f32 v[146:147], v[62:63], v[230:231], v[134:135]
	v_pk_fma_f32 v[66:67], v[56:57], v[236:237], v[66:67]
	v_pk_fma_f32 v[148:149], v[44:45], v[240:241], v[148:149]
	v_pk_fma_f32 v[162:163], v[34:35], v[250:251], v[162:163]
	v_pk_fma_f32 v[146:147], v[58:59], v[238:239], v[146:147]
	v_pk_fma_f32 v[66:67], v[48:49], v[244:245], v[66:67]
	v_pk_fma_f32 v[148:149], v[40:41], v[248:249], v[148:149]
	v_lshlrev_b32_e32 v228, 16, v96
	v_and_b32_e32 v229, 0xffff0000, v96
	v_lshlrev_b32_e32 v232, 16, v98
	v_and_b32_e32 v233, 0xffff0000, v98
	v_cvt_pk_bf16_f32 v227, v162, v163
	v_pk_fma_f32 v[162:163], v[54:55], v[234:235], v[130:131]
	v_pk_fma_f32 v[146:147], v[50:51], v[246:247], v[146:147]
	v_pk_fma_f32 v[66:67], v[36:37], v[228:229], v[66:67]
	v_lshlrev_b32_e32 v230, 16, v97
	v_and_b32_e32 v231, 0xffff0000, v97
	v_pk_fma_f32 v[148:149], v[32:33], v[232:233], v[148:149]
	ds_write_b128 v166, v[224:227] offset:816
	v_pk_fma_f32 v[162:163], v[46:47], v[242:243], v[162:163]
	v_pk_fma_f32 v[146:147], v[38:39], v[230:231], v[146:147]
	v_cvt_pk_bf16_f32 v224, v66, v67
	v_pk_fma_f32 v[66:67], v[60:61], v[236:237], v[132:133]
	v_cvt_pk_bf16_f32 v225, v146, v147
	v_cvt_pk_bf16_f32 v226, v148, v149
	v_pk_fma_f32 v[148:149], v[52:53], v[240:241], v[128:129]
	v_pk_fma_f32 v[162:163], v[42:43], v[250:251], v[162:163]
	v_lshlrev_b32_e32 v234, 16, v99
	v_and_b32_e32 v235, 0xffff0000, v99
	v_pk_fma_f32 v[146:147], v[62:63], v[238:239], v[134:135]
	v_pk_fma_f32 v[66:67], v[56:57], v[244:245], v[66:67]
	v_pk_fma_f32 v[148:149], v[44:45], v[248:249], v[148:149]
	v_pk_fma_f32 v[162:163], v[34:35], v[234:235], v[162:163]
	v_pk_fma_f32 v[146:147], v[58:59], v[246:247], v[146:147]
	v_pk_fma_f32 v[66:67], v[48:49], v[228:229], v[66:67]
	v_pk_fma_f32 v[148:149], v[40:41], v[232:233], v[148:149]
	v_lshlrev_b32_e32 v236, 16, v100
	v_and_b32_e32 v237, 0xffff0000, v100
	v_lshlrev_b32_e32 v240, 16, v102
	v_and_b32_e32 v241, 0xffff0000, v102
	v_cvt_pk_bf16_f32 v227, v162, v163
	v_pk_fma_f32 v[162:163], v[54:55], v[242:243], v[130:131]
	v_pk_fma_f32 v[146:147], v[50:51], v[230:231], v[146:147]
	v_pk_fma_f32 v[66:67], v[36:37], v[236:237], v[66:67]
	v_lshlrev_b32_e32 v238, 16, v101
	v_and_b32_e32 v239, 0xffff0000, v101
	v_pk_fma_f32 v[148:149], v[32:33], v[240:241], v[148:149]
	s_and_b64 s[18:19], s[18:19], s[20:21]
	ds_write_b128 v166, v[224:227] offset:1088
	v_pk_fma_f32 v[162:163], v[46:47], v[250:251], v[162:163]
	v_pk_fma_f32 v[146:147], v[38:39], v[238:239], v[146:147]
	v_cvt_pk_bf16_f32 v224, v66, v67
	v_pk_fma_f32 v[66:67], v[60:61], v[244:245], v[132:133]
	v_cvt_pk_bf16_f32 v225, v146, v147
	v_cvt_pk_bf16_f32 v226, v148, v149
	v_pk_fma_f32 v[148:149], v[52:53], v[248:249], v[128:129]
	v_pk_fma_f32 v[60:61], v[60:61], v[228:229], v[132:133]
	v_pk_fma_f32 v[52:53], v[52:53], v[232:233], v[128:129]
	s_waitcnt vmcnt(0)
; #define LAS __attribute__((address_space(3)))
; __device__ __forceinline__ unsigned cvt_pk_bf16(float lo, float hi) { unsigned r; asm volatile("v_cvt_pk_bf16_f32 %0, %1, %2" : "=v"(r) : "v"(lo), "v"(hi)); return r; }
; __device__ __forceinline__ float bf_lo(unsigned u) { return __uint_as_float(u << 16); }
; __device__ __forceinline__ float bf_hi(unsigned u) { return __uint_as_float(u & 0xffff0000u); }
; template <int dir>
; __device__ __forceinline__ void lru_pass(LAS unsigned char* lds, const Params& P, int b, int h, int q, bool dry) {
;     ...
;             for (int j = 0; j < 8; ++j) {
;                 f32x2 o0 = cb2[0], o1 = cb2[1], o2 = cb2[2], o3 = cb2[3];
; #pragma unroll
;                 for (int k = 0; k < 4; ++k) { const u32x4 rr = rows[j + k];
;                     o0 = cw2[k][0] * (f32x2){bf_lo(rr.x), bf_hi(rr.x)} + o0; o1 = cw2[k][1] * (f32x2){bf_lo(rr.y), bf_hi(rr.y)} + o1;
;                     o2 = cw2[k][2] * (f32x2){bf_lo(rr.z), bf_hi(rr.z)} + o2; o3 = cw2[k][3] * (f32x2){bf_lo(rr.w), bf_hi(rr.w)} + o3; }
;                 u32x4 w; w.x = cvt_pk_bf16(o0[0], o0[1]); w.y = cvt_pk_bf16(o1[0], o1[1]); w.z = cvt_pk_bf16(o2[0], o2[1]); w.w = cvt_pk_bf16(o3[0], o3[1]);
;                 *(LAS u32x4*)(XC + (tr * 8 + j) * XC_PITCH + cgp * 16) = w;
;             }
; #pragma unroll
;             for (int i = 0; i < NIN; ++i) { const int id = tid + i * NTHREADS;
;                 if (dir == 0) *(LAS u32x4*)(TIN + (id >> 2) * IO_NP + (id & 3) * 16) = inr[i];
;                 else *(LAS u32x4*)(TIN + (id >> 3) * IO_WP + (id & 7) * 16) = inr[i]; }
;             LruTile nxt = cur;
;             if (sc < 8) { nxt = lru_tile(Z, ZC, b, h, dir, sc + 1); lru_load_rows(rows, nxt, tr, cgp);
; #pragma unroll
;                 for (int i = 0; i < NIN; ++i) { const int id = tid + i * NTHREADS;
;                     if (dir == 0) inr[i] = *(const u32x4*)(Zg + (size_t)(nxt.t0 + (id >> 2)) * 128 + (id & 3) * 8);
;                     else inr[i] = *(const u32x4*)(Hg + (size_t)(nxt.t0 + (id >> 3)) * DM + (id & 7) * 4); } }
	v_cndmask_b32_e64 v108, 0, v108, s[18:19]
	v_pk_fma_f32 v[162:163], v[42:43], v[234:235], v[162:163]
	v_lshlrev_b32_e32 v242, 16, v103
	v_and_b32_e32 v243, 0xffff0000, v103
	v_pk_fma_f32 v[146:147], v[62:63], v[246:247], v[134:135]
	v_pk_fma_f32 v[66:67], v[56:57], v[228:229], v[66:67]
	v_pk_fma_f32 v[148:149], v[44:45], v[232:233], v[148:149]
	v_lshlrev_b32_e32 v244, 16, v104
	v_and_b32_e32 v245, 0xffff0000, v104
	v_lshlrev_b32_e32 v248, 16, v106
	v_and_b32_e32 v249, 0xffff0000, v106
	v_pk_fma_f32 v[62:63], v[62:63], v[230:231], v[134:135]
	v_pk_fma_f32 v[56:57], v[56:57], v[236:237], v[60:61]
	v_pk_fma_f32 v[44:45], v[44:45], v[240:241], v[52:53]
	v_cndmask_b32_e64 v109, 0, v109, s[18:19]
	v_pk_fma_f32 v[162:163], v[34:35], v[242:243], v[162:163]
	v_pk_fma_f32 v[146:147], v[58:59], v[230:231], v[146:147]
	v_pk_fma_f32 v[66:67], v[48:49], v[236:237], v[66:67]
	v_pk_fma_f32 v[148:149], v[40:41], v[240:241], v[148:149]
	v_lshlrev_b32_e32 v246, 16, v105
	v_and_b32_e32 v247, 0xffff0000, v105
	v_pk_fma_f32 v[58:59], v[58:59], v[238:239], v[62:63]
	v_pk_fma_f32 v[48:49], v[48:49], v[244:245], v[56:57]
	v_pk_fma_f32 v[40:41], v[40:41], v[248:249], v[44:45]
	v_lshlrev_b32_e32 v44, 16, v108
	v_and_b32_e32 v45, 0xffff0000, v108
	v_cndmask_b32_e64 v110, 0, v110, s[18:19]
	v_cvt_pk_bf16_f32 v227, v162, v163
	v_pk_fma_f32 v[162:163], v[54:55], v[250:251], v[130:131]
	v_pk_fma_f32 v[146:147], v[50:51], v[238:239], v[146:147]
	v_pk_fma_f32 v[66:67], v[36:37], v[244:245], v[66:67]
	v_pk_fma_f32 v[54:55], v[54:55], v[234:235], v[130:131]
	v_pk_fma_f32 v[50:51], v[50:51], v[246:247], v[58:59]
	v_pk_fma_f32 v[36:37], v[36:37], v[44:45], v[48:49]
	v_lshlrev_b32_e32 v44, 16, v109
	v_and_b32_e32 v45, 0xffff0000, v109
	v_cndmask_b32_e64 v111, 0, v111, s[18:19]
	v_pk_fma_f32 v[162:163], v[46:47], v[234:235], v[162:163]
	v_pk_fma_f32 v[146:147], v[38:39], v[246:247], v[146:147]
	v_lshlrev_b32_e32 v250, 16, v107
	v_and_b32_e32 v251, 0xffff0000, v107
	v_pk_fma_f32 v[46:47], v[46:47], v[242:243], v[54:55]
	v_pk_fma_f32 v[38:39], v[38:39], v[44:45], v[50:51]
	v_lshlrev_b32_e32 v44, 16, v110
	v_and_b32_e32 v45, 0xffff0000, v110
	v_pk_fma_f32 v[162:163], v[42:43], v[242:243], v[162:163]
	v_pk_fma_f32 v[148:149], v[32:33], v[248:249], v[148:149]
	v_pk_fma_f32 v[42:43], v[42:43], v[250:251], v[46:47]
	v_pk_fma_f32 v[40:41], v[32:33], v[44:45], v[40:41]
	v_lshlrev_b32_e32 v32, 16, v111
	v_and_b32_e32 v33, 0xffff0000, v111
	ds_write_b128 v166, v[224:227] offset:1360
	v_pk_fma_f32 v[162:163], v[34:35], v[250:251], v[162:163]
	v_cvt_pk_bf16_f32 v224, v66, v67
	v_cvt_pk_bf16_f32 v225, v146, v147
	v_cvt_pk_bf16_f32 v226, v148, v149
	v_pk_fma_f32 v[42:43], v[34:35], v[32:33], v[42:43]
	v_cvt_pk_bf16_f32 v227, v162, v163
	ds_write_b128 v166, v[224:227] offset:1632
	v_cvt_pk_bf16_f32 v32, v36, v37
	v_cvt_pk_bf16_f32 v33, v38, v39
	v_cvt_pk_bf16_f32 v34, v40, v41
	v_cvt_pk_bf16_f32 v35, v42, v43
	s_cmp_eq_u32 s44, 0xff800000
	ds_write_b128 v166, v[32:35] offset:1904
	ds_write_b128 v168, v[112:115]
	ds_write_b128 v169, v[116:119]
	ds_write_b128 v170, v[120:123]
	ds_write_b128 v171, v[124:127]
	s_cbranch_scc1 .LBB0_308
	global_load_dwordx4 v[68:71], v[144:145], off offset:-1280
	global_load_dwordx4 v[72:75], v[144:145], off offset:-1024
	global_load_dwordx4 v[76:79], v[144:145], off offset:-768
	global_load_dwordx4 v[80:83], v[144:145], off offset:-512
	global_load_dwordx4 v[84:87], v[144:145], off offset:-256
	global_load_dwordx4 v[88:91], v[144:145], off
	global_load_dwordx4 v[92:95], v[144:145], off offset:256
	global_load_dwordx4 v[96:99], v[144:145], off offset:512
	global_load_dwordx4 v[100:103], v[144:145], off offset:768
	global_load_dwordx4 v[104:107], v[144:145], off offset:1024
	global_load_dwordx4 v[108:111], v[144:145], off offset:1280
	v_lshl_add_u64 v[32:33], v[142:143], 0, s[44:45]
	v_lshl_add_u64 v[34:35], v[252:253], 0, s[44:45]
	global_load_dwordx4 v[112:115], v[32:33], off sc1
	global_load_dwordx4 v[116:119], v[34:35], off sc1
	v_lshl_add_u64 v[32:33], v[154:155], 0, s[44:45]
	v_lshl_add_u64 v[34:35], v[150:151], 0, s[44:45]
	global_load_dwordx4 v[120:123], v[32:33], off sc1
	global_load_dwordx4 v[124:127], v[34:35], off sc1
	s_movk_i32 s28, 0x800
	s_mov_b32 s20, s25
	s_branch .LBB0_309
